# v68: GEMM main loops: loop counter/pointer SALU moved in front of the loop-back barrier (back-edge rotation)
# baseline (speedup 1.0000x reference)
.LBB0_206:
	ds_read_b128 v[150:153], v167
	ds_read_b128 v[154:157], v167 offset:1024
	ds_read_b128 v[172:175], v167 offset:2048
	ds_read_b128 v[176:179], v167 offset:3072
	ds_read_b128 v[180:183], v168
	ds_read_b128 v[184:187], v168 offset:1024
	ds_read_b128 v[188:191], v168 offset:2048
	ds_read_b128 v[192:195], v168 offset:3072
	s_add_u32 s40, s38, 0xfff80080
	s_addc_u32 s41, s39, -1
	s_cmp_eq_u32 s64, 28
	s_cselect_b32 s43, s5, s41
	s_cselect_b32 s42, s29, s40
	s_cselect_b32 s41, s27, s45
	s_cselect_b32 s40, s37, s44
	v_lshl_add_u64 v[158:159], s[38:39], 0, v[142:143]
	s_add_i32 m0, s50, 0xc000
	ds_read_b128 v[196:199], v169
	ds_read_b128 v[200:203], v169 offset:1024
	ds_read_b128 v[204:207], v169 offset:2048
	ds_read_b128 v[208:211], v169 offset:3072
	ds_read_b128 v[214:217], v169 offset:4096
	ds_read_b128 v[218:221], v169 offset:5120
	ds_read_b128 v[222:225], v169 offset:6144
	ds_read_b128 v[226:229], v169 offset:7168
	global_load_lds_dwordx4 v[158:159], off
	v_lshl_add_u64 v[158:159], s[38:39], 0, v[144:145]
	s_add_i32 m0, s50, 0xe000
	s_nop 0
	global_load_lds_dwordx4 v[158:159], off
	s_waitcnt vmcnt(8)
	s_waitcnt lgkmcnt(0)
	s_barrier
	s_setprio 1
	s_waitcnt lgkmcnt(0)
	v_mfma_f32_16x16x32_bf16 v[126:129], v[150:153], v[196:199], v[126:129]
	v_mfma_f32_16x16x32_bf16 v[122:125], v[172:175], v[196:199], v[122:125]
	v_mfma_f32_16x16x32_bf16 v[110:113], v[150:153], v[204:207], v[110:113]
	v_mfma_f32_16x16x32_bf16 v[106:109], v[172:175], v[204:207], v[106:109]
	v_mfma_f32_16x16x32_bf16 v[94:97], v[150:153], v[214:217], v[94:97]
	v_mfma_f32_16x16x32_bf16 v[90:93], v[172:175], v[214:217], v[90:93]
	v_mfma_f32_16x16x32_bf16 v[78:81], v[150:153], v[222:225], v[78:81]
	v_mfma_f32_16x16x32_bf16 v[74:77], v[172:175], v[222:225], v[74:77]
	v_mfma_f32_16x16x32_bf16 v[126:129], v[154:157], v[200:203], v[126:129]
	v_mfma_f32_16x16x32_bf16 v[122:125], v[176:179], v[200:203], v[122:125]
	v_mfma_f32_16x16x32_bf16 v[110:113], v[154:157], v[208:211], v[110:113]
	v_mfma_f32_16x16x32_bf16 v[106:109], v[176:179], v[208:211], v[106:109]
	v_mfma_f32_16x16x32_bf16 v[94:97], v[154:157], v[218:221], v[94:97]
	v_mfma_f32_16x16x32_bf16 v[90:93], v[176:179], v[218:221], v[90:93]
	v_mfma_f32_16x16x32_bf16 v[78:81], v[154:157], v[226:229], v[78:81]
	v_mfma_f32_16x16x32_bf16 v[74:77], v[176:179], v[226:229], v[74:77]
	s_setprio 0
	s_setprio 1
	v_mfma_f32_16x16x32_bf16 v[118:121], v[180:183], v[196:199], v[118:121]
	v_mfma_f32_16x16x32_bf16 v[114:117], v[188:191], v[196:199], v[114:117]
	v_mfma_f32_16x16x32_bf16 v[102:105], v[180:183], v[204:207], v[102:105]
	v_mfma_f32_16x16x32_bf16 v[98:101], v[188:191], v[204:207], v[98:101]
	v_mfma_f32_16x16x32_bf16 v[86:89], v[180:183], v[214:217], v[86:89]
	v_mfma_f32_16x16x32_bf16 v[82:85], v[188:191], v[214:217], v[82:85]
	v_mfma_f32_16x16x32_bf16 v[70:73], v[180:183], v[222:225], v[70:73]
	v_mfma_f32_16x16x32_bf16 v[66:69], v[188:191], v[222:225], v[66:69]
	v_mfma_f32_16x16x32_bf16 v[118:121], v[184:187], v[200:203], v[118:121]
	v_mfma_f32_16x16x32_bf16 v[114:117], v[192:195], v[200:203], v[114:117]
	v_mfma_f32_16x16x32_bf16 v[102:105], v[184:187], v[208:211], v[102:105]
	v_mfma_f32_16x16x32_bf16 v[98:101], v[192:195], v[208:211], v[98:101]
	v_mfma_f32_16x16x32_bf16 v[86:89], v[184:187], v[218:221], v[86:89]
	v_mfma_f32_16x16x32_bf16 v[82:85], v[192:195], v[218:221], v[82:85]
	v_mfma_f32_16x16x32_bf16 v[70:73], v[184:187], v[226:229], v[70:73]
	v_mfma_f32_16x16x32_bf16 v[66:69], v[192:195], v[226:229], v[66:69]
	s_setprio 0
	s_barrier
	s_add_i32 s65, s60, s49
	v_lshl_add_u64 v[158:159], s[40:41], 0, v[132:133]
	s_mov_b32 m0, s65
	ds_read_b128 v[196:199], v169 offset:16384
	ds_read_b128 v[200:203], v169 offset:17408
	ds_read_b128 v[204:207], v169 offset:18432
	ds_read_b128 v[208:211], v169 offset:19456
	ds_read_b128 v[214:217], v169 offset:20480
	ds_read_b128 v[218:221], v169 offset:21504
	ds_read_b128 v[222:225], v169 offset:22528
	ds_read_b128 v[226:229], v169 offset:23552
	global_load_lds_dwordx4 v[158:159], off
	s_add_i32 m0, s65, 0x2000
	s_add_u32 s66, s40, 0x80000
	v_lshl_add_u64 v[230:231], s[40:41], 0, v[136:137]
	s_addc_u32 s67, s41, 0
	s_add_i32 s65, s61, s49
	global_load_lds_dwordx4 v[230:231], off
	v_lshl_add_u64 v[232:233], s[66:67], 0, v[132:133]
	s_mov_b32 m0, s65
	v_lshl_add_u64 v[234:235], s[42:43], 0, v[134:135]
	global_load_lds_dwordx4 v[232:233], off
	v_lshl_add_u64 v[232:233], s[66:67], 0, v[136:137]
	s_add_i32 m0, s65, 0x2000
	s_nop 0
	global_load_lds_dwordx4 v[232:233], off
	v_lshl_add_u64 v[232:233], s[42:43], 0, v[130:131]
	s_mov_b32 m0, s50
	s_nop 0
	global_load_lds_dwordx4 v[232:233], off
	s_mov_b32 m0, s51
	s_nop 0
	global_load_lds_dwordx4 v[234:235], off
	s_waitcnt vmcnt(8)
	s_waitcnt lgkmcnt(0)
	s_barrier
	s_setprio 1
	s_waitcnt lgkmcnt(0)
	v_mfma_f32_16x16x32_bf16 v[62:65], v[150:153], v[196:199], v[62:65]
	v_mfma_f32_16x16x32_bf16 v[58:61], v[172:175], v[196:199], v[58:61]
	v_mfma_f32_16x16x32_bf16 v[46:49], v[150:153], v[204:207], v[46:49]
	v_mfma_f32_16x16x32_bf16 v[42:45], v[172:175], v[204:207], v[42:45]
	v_mfma_f32_16x16x32_bf16 v[30:33], v[150:153], v[214:217], v[30:33]
	v_mfma_f32_16x16x32_bf16 v[26:29], v[172:175], v[214:217], v[26:29]
	v_mfma_f32_16x16x32_bf16 v[14:17], v[150:153], v[222:225], v[14:17]
	v_mfma_f32_16x16x32_bf16 v[10:13], v[172:175], v[222:225], v[10:13]
	v_mfma_f32_16x16x32_bf16 v[62:65], v[154:157], v[200:203], v[62:65]
	v_mfma_f32_16x16x32_bf16 v[58:61], v[176:179], v[200:203], v[58:61]
	v_mfma_f32_16x16x32_bf16 v[46:49], v[154:157], v[208:211], v[46:49]
	v_mfma_f32_16x16x32_bf16 v[42:45], v[176:179], v[208:211], v[42:45]
	v_mfma_f32_16x16x32_bf16 v[30:33], v[154:157], v[218:221], v[30:33]
	v_mfma_f32_16x16x32_bf16 v[26:29], v[176:179], v[218:221], v[26:29]
	v_mfma_f32_16x16x32_bf16 v[14:17], v[154:157], v[226:229], v[14:17]
	v_mfma_f32_16x16x32_bf16 v[10:13], v[176:179], v[226:229], v[10:13]
	s_setprio 0
	s_setprio 1
	v_mfma_f32_16x16x32_bf16 v[54:57], v[180:183], v[196:199], v[54:57]
	v_mfma_f32_16x16x32_bf16 v[50:53], v[188:191], v[196:199], v[50:53]
	v_mfma_f32_16x16x32_bf16 v[38:41], v[180:183], v[204:207], v[38:41]
	v_mfma_f32_16x16x32_bf16 v[34:37], v[188:191], v[204:207], v[34:37]
	v_mfma_f32_16x16x32_bf16 v[22:25], v[180:183], v[214:217], v[22:25]
	v_mfma_f32_16x16x32_bf16 v[18:21], v[188:191], v[214:217], v[18:21]
	v_mfma_f32_16x16x32_bf16 v[6:9], v[180:183], v[222:225], v[6:9]
	v_mfma_f32_16x16x32_bf16 v[2:5], v[188:191], v[222:225], v[2:5]
	v_mfma_f32_16x16x32_bf16 v[54:57], v[184:187], v[200:203], v[54:57]
	v_mfma_f32_16x16x32_bf16 v[50:53], v[192:195], v[200:203], v[50:53]
	v_mfma_f32_16x16x32_bf16 v[38:41], v[184:187], v[208:211], v[38:41]
	v_mfma_f32_16x16x32_bf16 v[34:37], v[192:195], v[208:211], v[34:37]
	v_mfma_f32_16x16x32_bf16 v[22:25], v[184:187], v[218:221], v[22:25]
	v_mfma_f32_16x16x32_bf16 v[18:21], v[192:195], v[218:221], v[18:21]
	v_mfma_f32_16x16x32_bf16 v[6:9], v[184:187], v[226:229], v[6:9]
	v_mfma_f32_16x16x32_bf16 v[2:5], v[192:195], v[226:229], v[2:5]
	s_setprio 0
	s_barrier
	s_add_i32 s65, 0, 0x18000
	v_add_u32_e32 v138, s65, v165
	s_add_i32 s66, 0, 0x1c000
	ds_read_b128 v[150:153], v138
	ds_read_b128 v[154:157], v138 offset:1024
	ds_read_b128 v[172:175], v138 offset:2048
	ds_read_b128 v[176:179], v138 offset:3072
	v_add_u32_e32 v138, s66, v165
	ds_read_b128 v[180:183], v138
	ds_read_b128 v[184:187], v138 offset:1024
	ds_read_b128 v[188:191], v138 offset:2048
	ds_read_b128 v[192:195], v138 offset:3072
	s_add_u32 s42, s42, 0x80000
	s_addc_u32 s43, s43, 0
	s_mov_b32 m0, s52
	v_lshl_add_u64 v[236:237], s[42:43], 0, v[130:131]
	ds_read_b128 v[196:199], v169 offset:32768
	ds_read_b128 v[200:203], v169 offset:33792
	ds_read_b128 v[204:207], v169 offset:34816
	ds_read_b128 v[208:211], v169 offset:35840
	ds_read_b128 v[214:217], v169 offset:36864
	ds_read_b128 v[218:221], v169 offset:37888
	ds_read_b128 v[222:225], v169 offset:38912
	ds_read_b128 v[226:229], v169 offset:39936
	global_load_lds_dwordx4 v[236:237], off
	v_lshl_add_u64 v[236:237], s[42:43], 0, v[134:135]
	s_mov_b32 m0, s53
	s_nop 0
	global_load_lds_dwordx4 v[236:237], off
	s_waitcnt vmcnt(8)
	s_waitcnt lgkmcnt(0)
	s_barrier
	s_setprio 1
	s_waitcnt lgkmcnt(0)
	v_mfma_f32_16x16x32_bf16 v[126:129], v[150:153], v[196:199], v[126:129]
	v_mfma_f32_16x16x32_bf16 v[122:125], v[172:175], v[196:199], v[122:125]
	v_mfma_f32_16x16x32_bf16 v[110:113], v[150:153], v[204:207], v[110:113]
	v_mfma_f32_16x16x32_bf16 v[106:109], v[172:175], v[204:207], v[106:109]
	v_mfma_f32_16x16x32_bf16 v[94:97], v[150:153], v[214:217], v[94:97]
	v_mfma_f32_16x16x32_bf16 v[90:93], v[172:175], v[214:217], v[90:93]
	v_mfma_f32_16x16x32_bf16 v[78:81], v[150:153], v[222:225], v[78:81]
	v_mfma_f32_16x16x32_bf16 v[74:77], v[172:175], v[222:225], v[74:77]
	v_mfma_f32_16x16x32_bf16 v[126:129], v[154:157], v[200:203], v[126:129]
	v_mfma_f32_16x16x32_bf16 v[122:125], v[176:179], v[200:203], v[122:125]
	v_mfma_f32_16x16x32_bf16 v[110:113], v[154:157], v[208:211], v[110:113]
	v_mfma_f32_16x16x32_bf16 v[106:109], v[176:179], v[208:211], v[106:109]
	v_mfma_f32_16x16x32_bf16 v[94:97], v[154:157], v[218:221], v[94:97]
	v_mfma_f32_16x16x32_bf16 v[90:93], v[176:179], v[218:221], v[90:93]
	v_mfma_f32_16x16x32_bf16 v[78:81], v[154:157], v[226:229], v[78:81]
	v_mfma_f32_16x16x32_bf16 v[74:77], v[176:179], v[226:229], v[74:77]
	s_setprio 0
	s_setprio 1
	v_mfma_f32_16x16x32_bf16 v[118:121], v[180:183], v[196:199], v[118:121]
	v_mfma_f32_16x16x32_bf16 v[114:117], v[188:191], v[196:199], v[114:117]
	v_mfma_f32_16x16x32_bf16 v[102:105], v[180:183], v[204:207], v[102:105]
	v_mfma_f32_16x16x32_bf16 v[98:101], v[188:191], v[204:207], v[98:101]
	v_mfma_f32_16x16x32_bf16 v[86:89], v[180:183], v[214:217], v[86:89]
	v_mfma_f32_16x16x32_bf16 v[82:85], v[188:191], v[214:217], v[82:85]
	v_mfma_f32_16x16x32_bf16 v[70:73], v[180:183], v[222:225], v[70:73]
	v_mfma_f32_16x16x32_bf16 v[66:69], v[188:191], v[222:225], v[66:69]
	v_mfma_f32_16x16x32_bf16 v[118:121], v[184:187], v[200:203], v[118:121]
	v_mfma_f32_16x16x32_bf16 v[114:117], v[192:195], v[200:203], v[114:117]
	v_mfma_f32_16x16x32_bf16 v[102:105], v[184:187], v[208:211], v[102:105]
	v_mfma_f32_16x16x32_bf16 v[98:101], v[192:195], v[208:211], v[98:101]
	v_mfma_f32_16x16x32_bf16 v[86:89], v[184:187], v[218:221], v[86:89]
	v_mfma_f32_16x16x32_bf16 v[82:85], v[192:195], v[218:221], v[82:85]
	v_mfma_f32_16x16x32_bf16 v[70:73], v[184:187], v[226:229], v[70:73]
	v_mfma_f32_16x16x32_bf16 v[66:69], v[192:195], v[226:229], v[66:69]
	s_setprio 0
	s_barrier
	s_add_i32 s42, s65, s49
	v_lshl_add_u64 v[158:159], v[158:159], 0, s[20:21]
	s_mov_b32 m0, s42
	ds_read_b128 v[196:199], v169 offset:49152
	ds_read_b128 v[200:203], v169 offset:50176
	ds_read_b128 v[204:207], v169 offset:51200
	ds_read_b128 v[208:211], v169 offset:52224
	ds_read_b128 v[214:217], v169 offset:53248
	ds_read_b128 v[218:221], v169 offset:54272
	ds_read_b128 v[222:225], v169 offset:55296
	ds_read_b128 v[226:229], v169 offset:56320
	global_load_lds_dwordx4 v[158:159], off
	s_add_i32 m0, s42, 0x2000
	s_add_u32 s40, s40, 0x80080
	v_lshl_add_u64 v[158:159], v[230:231], 0, s[20:21]
	s_addc_u32 s41, s41, 0
	s_add_i32 s42, s66, s49
	global_load_lds_dwordx4 v[158:159], off
	v_lshl_add_u64 v[158:159], s[40:41], 0, v[132:133]
	s_mov_b32 m0, s42
	s_nop 0
	global_load_lds_dwordx4 v[158:159], off
	v_lshl_add_u64 v[158:159], s[40:41], 0, v[136:137]
	s_add_i32 m0, s42, 0x2000
	s_nop 0
	global_load_lds_dwordx4 v[158:159], off
	v_lshl_add_u64 v[158:159], v[232:233], 0, s[20:21]
	s_mov_b32 m0, s56
	s_nop 0
	global_load_lds_dwordx4 v[158:159], off
	v_lshl_add_u64 v[158:159], v[234:235], 0, s[20:21]
	s_mov_b32 m0, s57
	s_nop 0
	global_load_lds_dwordx4 v[158:159], off
	s_waitcnt vmcnt(8)
	s_waitcnt lgkmcnt(0)
	s_barrier
	s_setprio 1
	s_waitcnt lgkmcnt(0)
	v_mfma_f32_16x16x32_bf16 v[62:65], v[150:153], v[196:199], v[62:65]
	v_mfma_f32_16x16x32_bf16 v[58:61], v[172:175], v[196:199], v[58:61]
	v_mfma_f32_16x16x32_bf16 v[46:49], v[150:153], v[204:207], v[46:49]
	v_mfma_f32_16x16x32_bf16 v[42:45], v[172:175], v[204:207], v[42:45]
	v_mfma_f32_16x16x32_bf16 v[30:33], v[150:153], v[214:217], v[30:33]
	v_mfma_f32_16x16x32_bf16 v[26:29], v[172:175], v[214:217], v[26:29]
	v_mfma_f32_16x16x32_bf16 v[14:17], v[150:153], v[222:225], v[14:17]
	v_mfma_f32_16x16x32_bf16 v[10:13], v[172:175], v[222:225], v[10:13]
	v_mfma_f32_16x16x32_bf16 v[62:65], v[154:157], v[200:203], v[62:65]
	v_mfma_f32_16x16x32_bf16 v[58:61], v[176:179], v[200:203], v[58:61]
	v_mfma_f32_16x16x32_bf16 v[46:49], v[154:157], v[208:211], v[46:49]
	v_mfma_f32_16x16x32_bf16 v[42:45], v[176:179], v[208:211], v[42:45]
	v_mfma_f32_16x16x32_bf16 v[30:33], v[154:157], v[218:221], v[30:33]
	v_mfma_f32_16x16x32_bf16 v[26:29], v[176:179], v[218:221], v[26:29]
	v_mfma_f32_16x16x32_bf16 v[14:17], v[154:157], v[226:229], v[14:17]
	v_mfma_f32_16x16x32_bf16 v[10:13], v[176:179], v[226:229], v[10:13]
	s_setprio 0
	s_setprio 1
	v_mfma_f32_16x16x32_bf16 v[54:57], v[180:183], v[196:199], v[54:57]
	v_mfma_f32_16x16x32_bf16 v[50:53], v[188:191], v[196:199], v[50:53]
	v_mfma_f32_16x16x32_bf16 v[38:41], v[180:183], v[204:207], v[38:41]
	v_mfma_f32_16x16x32_bf16 v[34:37], v[188:191], v[204:207], v[34:37]
	v_mfma_f32_16x16x32_bf16 v[22:25], v[180:183], v[214:217], v[22:25]
	v_mfma_f32_16x16x32_bf16 v[18:21], v[188:191], v[214:217], v[18:21]
	v_mfma_f32_16x16x32_bf16 v[6:9], v[180:183], v[222:225], v[6:9]
	v_mfma_f32_16x16x32_bf16 v[2:5], v[188:191], v[222:225], v[2:5]
	v_mfma_f32_16x16x32_bf16 v[54:57], v[184:187], v[200:203], v[54:57]
	v_mfma_f32_16x16x32_bf16 v[50:53], v[192:195], v[200:203], v[50:53]
	v_mfma_f32_16x16x32_bf16 v[38:41], v[184:187], v[208:211], v[38:41]
	v_mfma_f32_16x16x32_bf16 v[34:37], v[192:195], v[208:211], v[34:37]
	v_mfma_f32_16x16x32_bf16 v[22:25], v[184:187], v[218:221], v[22:25]
	v_mfma_f32_16x16x32_bf16 v[18:21], v[192:195], v[218:221], v[18:21]
	v_mfma_f32_16x16x32_bf16 v[6:9], v[184:187], v[226:229], v[6:9]
	v_mfma_f32_16x16x32_bf16 v[2:5], v[192:195], v[226:229], v[2:5]
	s_setprio 0
	s_add_i32 s64, s64, 2
	s_add_u32 s38, s38, 0x100
	s_addc_u32 s39, s39, 0
	s_add_u32 s44, s44, 0x100
	s_addc_u32 s45, s45, 0
	s_cmp_gt_u32 s64, 29
	s_barrier
	s_cbranch_scc0 .LBB0_206
	s_and_b64 vcc, exec, s[22:23]
	s_cbranch_vccz .LBB0_209
	s_barrier

.LBB0_1517:
	ds_read_b128 v[146:149], v154
	ds_read_b128 v[158:161], v154 offset:1024
	ds_read_b128 v[162:165], v154 offset:2048
	ds_read_b128 v[166:169], v154 offset:3072
	ds_read_b128 v[170:173], v155
	ds_read_b128 v[174:177], v155 offset:1024
	ds_read_b128 v[178:181], v155 offset:2048
	ds_read_b128 v[182:185], v155 offset:3072
	s_add_u32 s28, s26, 0xfff80080
	s_addc_u32 s29, s27, -1
	s_cmp_eq_u32 s51, 28
	s_cselect_b32 s31, s17, s29
	s_cselect_b32 s30, s23, s28
	s_cselect_b32 s29, s15, s50
	s_cselect_b32 s28, s48, s49
	v_lshl_add_u64 v[210:211], s[26:27], 0, v[138:139]
	s_add_i32 m0, s25, 0xc000
	ds_read_b128 v[186:189], v156
	ds_read_b128 v[190:193], v156 offset:1024
	ds_read_b128 v[194:197], v156 offset:2048
	ds_read_b128 v[198:201], v156 offset:3072
	ds_read_b128 v[202:205], v156 offset:4096
	ds_read_b128 v[206:209], v156 offset:5120
	ds_read_b128 v[214:217], v156 offset:6144
	ds_read_b128 v[218:221], v156 offset:7168
	global_load_lds_dwordx4 v[210:211], off
	v_lshl_add_u64 v[210:211], s[26:27], 0, v[140:141]
	s_add_i32 m0, s25, 0xe000
	s_nop 0
	global_load_lds_dwordx4 v[210:211], off
	s_waitcnt vmcnt(8)
	s_waitcnt lgkmcnt(0)
	s_barrier
	s_setprio 1
	s_waitcnt lgkmcnt(0)
	v_mfma_f32_16x16x32_bf16 v[126:129], v[146:149], v[186:189], v[126:129]
	v_mfma_f32_16x16x32_bf16 v[122:125], v[162:165], v[186:189], v[122:125]
	v_mfma_f32_16x16x32_bf16 v[110:113], v[146:149], v[194:197], v[110:113]
	v_mfma_f32_16x16x32_bf16 v[106:109], v[162:165], v[194:197], v[106:109]
	v_mfma_f32_16x16x32_bf16 v[94:97], v[146:149], v[202:205], v[94:97]
	v_mfma_f32_16x16x32_bf16 v[90:93], v[162:165], v[202:205], v[90:93]
	v_mfma_f32_16x16x32_bf16 v[78:81], v[146:149], v[214:217], v[78:81]
	v_mfma_f32_16x16x32_bf16 v[74:77], v[162:165], v[214:217], v[74:77]
	v_mfma_f32_16x16x32_bf16 v[126:129], v[158:161], v[190:193], v[126:129]
	v_mfma_f32_16x16x32_bf16 v[122:125], v[166:169], v[190:193], v[122:125]
	v_mfma_f32_16x16x32_bf16 v[110:113], v[158:161], v[198:201], v[110:113]
	v_mfma_f32_16x16x32_bf16 v[106:109], v[166:169], v[198:201], v[106:109]
	v_mfma_f32_16x16x32_bf16 v[94:97], v[158:161], v[206:209], v[94:97]
	v_mfma_f32_16x16x32_bf16 v[90:93], v[166:169], v[206:209], v[90:93]
	v_mfma_f32_16x16x32_bf16 v[78:81], v[158:161], v[218:221], v[78:81]
	v_mfma_f32_16x16x32_bf16 v[74:77], v[166:169], v[218:221], v[74:77]
	s_setprio 0
	s_setprio 1
	v_mfma_f32_16x16x32_bf16 v[118:121], v[170:173], v[186:189], v[118:121]
	v_mfma_f32_16x16x32_bf16 v[114:117], v[178:181], v[186:189], v[114:117]
	v_mfma_f32_16x16x32_bf16 v[102:105], v[170:173], v[194:197], v[102:105]
	v_mfma_f32_16x16x32_bf16 v[98:101], v[178:181], v[194:197], v[98:101]
	v_mfma_f32_16x16x32_bf16 v[86:89], v[170:173], v[202:205], v[86:89]
	v_mfma_f32_16x16x32_bf16 v[82:85], v[178:181], v[202:205], v[82:85]
	v_mfma_f32_16x16x32_bf16 v[70:73], v[170:173], v[214:217], v[70:73]
	v_mfma_f32_16x16x32_bf16 v[66:69], v[178:181], v[214:217], v[66:69]
	v_mfma_f32_16x16x32_bf16 v[118:121], v[174:177], v[190:193], v[118:121]
	v_mfma_f32_16x16x32_bf16 v[114:117], v[182:185], v[190:193], v[114:117]
	v_mfma_f32_16x16x32_bf16 v[102:105], v[174:177], v[198:201], v[102:105]
	v_mfma_f32_16x16x32_bf16 v[98:101], v[182:185], v[198:201], v[98:101]
	v_mfma_f32_16x16x32_bf16 v[86:89], v[174:177], v[206:209], v[86:89]
	v_mfma_f32_16x16x32_bf16 v[82:85], v[182:185], v[206:209], v[82:85]
	v_mfma_f32_16x16x32_bf16 v[70:73], v[174:177], v[218:221], v[70:73]
	v_mfma_f32_16x16x32_bf16 v[66:69], v[182:185], v[218:221], v[66:69]
	s_setprio 0
	s_barrier
	s_add_i32 s52, s46, s37
	v_lshl_add_u64 v[210:211], s[28:29], 0, v[132:133]
	s_mov_b32 m0, s52
	ds_read_b128 v[186:189], v156 offset:16384
	ds_read_b128 v[190:193], v156 offset:17408
	ds_read_b128 v[194:197], v156 offset:18432
	ds_read_b128 v[198:201], v156 offset:19456
	ds_read_b128 v[202:205], v156 offset:20480
	ds_read_b128 v[206:209], v156 offset:21504
	ds_read_b128 v[214:217], v156 offset:22528
	ds_read_b128 v[218:221], v156 offset:23552
	global_load_lds_dwordx4 v[210:211], off
	s_add_i32 m0, s52, 0x2000
	s_add_u32 s52, s28, 0x80000
	v_lshl_add_u64 v[222:223], s[28:29], 0, v[136:137]
	s_addc_u32 s53, s29, 0
	s_add_i32 s54, s47, s37
	global_load_lds_dwordx4 v[222:223], off
	v_lshl_add_u64 v[224:225], s[52:53], 0, v[132:133]
	s_mov_b32 m0, s54
	v_lshl_add_u64 v[226:227], s[30:31], 0, v[134:135]
	global_load_lds_dwordx4 v[224:225], off
	v_lshl_add_u64 v[224:225], s[52:53], 0, v[136:137]
	s_add_i32 m0, s54, 0x2000
	s_nop 0
	global_load_lds_dwordx4 v[224:225], off
	v_lshl_add_u64 v[224:225], s[30:31], 0, v[130:131]
	s_mov_b32 m0, s25
	s_nop 0
	global_load_lds_dwordx4 v[224:225], off
	s_mov_b32 m0, s38
	s_nop 0
	global_load_lds_dwordx4 v[226:227], off
	s_waitcnt vmcnt(8)
	s_waitcnt lgkmcnt(0)
	s_barrier
	s_setprio 1
	s_waitcnt lgkmcnt(0)
	v_mfma_f32_16x16x32_bf16 v[62:65], v[146:149], v[186:189], v[62:65]
	v_mfma_f32_16x16x32_bf16 v[58:61], v[162:165], v[186:189], v[58:61]
	v_mfma_f32_16x16x32_bf16 v[46:49], v[146:149], v[194:197], v[46:49]
	v_mfma_f32_16x16x32_bf16 v[42:45], v[162:165], v[194:197], v[42:45]
	v_mfma_f32_16x16x32_bf16 v[30:33], v[146:149], v[202:205], v[30:33]
	v_mfma_f32_16x16x32_bf16 v[26:29], v[162:165], v[202:205], v[26:29]
	v_mfma_f32_16x16x32_bf16 v[14:17], v[146:149], v[214:217], v[14:17]
	v_mfma_f32_16x16x32_bf16 v[10:13], v[162:165], v[214:217], v[10:13]
	v_mfma_f32_16x16x32_bf16 v[62:65], v[158:161], v[190:193], v[62:65]
	v_mfma_f32_16x16x32_bf16 v[58:61], v[166:169], v[190:193], v[58:61]
	v_mfma_f32_16x16x32_bf16 v[46:49], v[158:161], v[198:201], v[46:49]
	v_mfma_f32_16x16x32_bf16 v[42:45], v[166:169], v[198:201], v[42:45]
	v_mfma_f32_16x16x32_bf16 v[30:33], v[158:161], v[206:209], v[30:33]
	v_mfma_f32_16x16x32_bf16 v[26:29], v[166:169], v[206:209], v[26:29]
	v_mfma_f32_16x16x32_bf16 v[14:17], v[158:161], v[218:221], v[14:17]
	v_mfma_f32_16x16x32_bf16 v[10:13], v[166:169], v[218:221], v[10:13]
	s_setprio 0
	s_setprio 1
	v_mfma_f32_16x16x32_bf16 v[54:57], v[170:173], v[186:189], v[54:57]
	v_mfma_f32_16x16x32_bf16 v[50:53], v[178:181], v[186:189], v[50:53]
	v_mfma_f32_16x16x32_bf16 v[38:41], v[170:173], v[194:197], v[38:41]
	v_mfma_f32_16x16x32_bf16 v[34:37], v[178:181], v[194:197], v[34:37]
	v_mfma_f32_16x16x32_bf16 v[22:25], v[170:173], v[202:205], v[22:25]
	v_mfma_f32_16x16x32_bf16 v[18:21], v[178:181], v[202:205], v[18:21]
	v_mfma_f32_16x16x32_bf16 v[6:9], v[170:173], v[214:217], v[6:9]
	v_mfma_f32_16x16x32_bf16 v[2:5], v[178:181], v[214:217], v[2:5]
	v_mfma_f32_16x16x32_bf16 v[54:57], v[174:177], v[190:193], v[54:57]
	v_mfma_f32_16x16x32_bf16 v[50:53], v[182:185], v[190:193], v[50:53]
	v_mfma_f32_16x16x32_bf16 v[38:41], v[174:177], v[198:201], v[38:41]
	v_mfma_f32_16x16x32_bf16 v[34:37], v[182:185], v[198:201], v[34:37]
	v_mfma_f32_16x16x32_bf16 v[22:25], v[174:177], v[206:209], v[22:25]
	v_mfma_f32_16x16x32_bf16 v[18:21], v[182:185], v[206:209], v[18:21]
	v_mfma_f32_16x16x32_bf16 v[6:9], v[174:177], v[218:221], v[6:9]
	v_mfma_f32_16x16x32_bf16 v[2:5], v[182:185], v[218:221], v[2:5]
	s_setprio 0
	s_barrier
	s_add_i32 s52, 0, 0x18000
	v_add_u32_e32 v157, s52, v152
	s_add_i32 s53, 0, 0x1c000
	ds_read_b128 v[146:149], v157
	ds_read_b128 v[158:161], v157 offset:1024
	ds_read_b128 v[162:165], v157 offset:2048
	ds_read_b128 v[166:169], v157 offset:3072
	v_add_u32_e32 v157, s53, v152
	ds_read_b128 v[170:173], v157
	ds_read_b128 v[174:177], v157 offset:1024
	ds_read_b128 v[178:181], v157 offset:2048
	ds_read_b128 v[182:185], v157 offset:3072
	s_add_u32 s30, s30, 0x80000
	s_addc_u32 s31, s31, 0
	s_mov_b32 m0, s39
	v_lshl_add_u64 v[228:229], s[30:31], 0, v[130:131]
	ds_read_b128 v[186:189], v156 offset:32768
	ds_read_b128 v[190:193], v156 offset:33792
	ds_read_b128 v[194:197], v156 offset:34816
	ds_read_b128 v[198:201], v156 offset:35840
	ds_read_b128 v[202:205], v156 offset:36864
	ds_read_b128 v[206:209], v156 offset:37888
	ds_read_b128 v[214:217], v156 offset:38912
	ds_read_b128 v[218:221], v156 offset:39936
	global_load_lds_dwordx4 v[228:229], off
	v_lshl_add_u64 v[228:229], s[30:31], 0, v[134:135]
	s_mov_b32 m0, s40
	s_nop 0
	global_load_lds_dwordx4 v[228:229], off
	s_waitcnt vmcnt(8)
	s_waitcnt lgkmcnt(0)
	s_barrier
	s_setprio 1
	s_waitcnt lgkmcnt(0)
	v_mfma_f32_16x16x32_bf16 v[126:129], v[146:149], v[186:189], v[126:129]
	v_mfma_f32_16x16x32_bf16 v[122:125], v[162:165], v[186:189], v[122:125]
	v_mfma_f32_16x16x32_bf16 v[110:113], v[146:149], v[194:197], v[110:113]
	v_mfma_f32_16x16x32_bf16 v[106:109], v[162:165], v[194:197], v[106:109]
	v_mfma_f32_16x16x32_bf16 v[94:97], v[146:149], v[202:205], v[94:97]
	v_mfma_f32_16x16x32_bf16 v[90:93], v[162:165], v[202:205], v[90:93]
	v_mfma_f32_16x16x32_bf16 v[78:81], v[146:149], v[214:217], v[78:81]
	v_mfma_f32_16x16x32_bf16 v[74:77], v[162:165], v[214:217], v[74:77]
	v_mfma_f32_16x16x32_bf16 v[126:129], v[158:161], v[190:193], v[126:129]
	v_mfma_f32_16x16x32_bf16 v[122:125], v[166:169], v[190:193], v[122:125]
	v_mfma_f32_16x16x32_bf16 v[110:113], v[158:161], v[198:201], v[110:113]
	v_mfma_f32_16x16x32_bf16 v[106:109], v[166:169], v[198:201], v[106:109]
	v_mfma_f32_16x16x32_bf16 v[94:97], v[158:161], v[206:209], v[94:97]
	v_mfma_f32_16x16x32_bf16 v[90:93], v[166:169], v[206:209], v[90:93]
	v_mfma_f32_16x16x32_bf16 v[78:81], v[158:161], v[218:221], v[78:81]
	v_mfma_f32_16x16x32_bf16 v[74:77], v[166:169], v[218:221], v[74:77]
	s_setprio 0
	s_setprio 1
	v_mfma_f32_16x16x32_bf16 v[118:121], v[170:173], v[186:189], v[118:121]
	v_mfma_f32_16x16x32_bf16 v[114:117], v[178:181], v[186:189], v[114:117]
	v_mfma_f32_16x16x32_bf16 v[102:105], v[170:173], v[194:197], v[102:105]
	v_mfma_f32_16x16x32_bf16 v[98:101], v[178:181], v[194:197], v[98:101]
	v_mfma_f32_16x16x32_bf16 v[86:89], v[170:173], v[202:205], v[86:89]
	v_mfma_f32_16x16x32_bf16 v[82:85], v[178:181], v[202:205], v[82:85]
	v_mfma_f32_16x16x32_bf16 v[70:73], v[170:173], v[214:217], v[70:73]
	v_mfma_f32_16x16x32_bf16 v[66:69], v[178:181], v[214:217], v[66:69]
	v_mfma_f32_16x16x32_bf16 v[118:121], v[174:177], v[190:193], v[118:121]
	v_mfma_f32_16x16x32_bf16 v[114:117], v[182:185], v[190:193], v[114:117]
	v_mfma_f32_16x16x32_bf16 v[102:105], v[174:177], v[198:201], v[102:105]
	v_mfma_f32_16x16x32_bf16 v[98:101], v[182:185], v[198:201], v[98:101]
	v_mfma_f32_16x16x32_bf16 v[86:89], v[174:177], v[206:209], v[86:89]
	v_mfma_f32_16x16x32_bf16 v[82:85], v[182:185], v[206:209], v[82:85]
	v_mfma_f32_16x16x32_bf16 v[70:73], v[174:177], v[218:221], v[70:73]
	v_mfma_f32_16x16x32_bf16 v[66:69], v[182:185], v[218:221], v[66:69]
	s_setprio 0
	s_barrier
	s_add_i32 s30, s52, s37
	v_lshl_add_u64 v[210:211], v[210:211], 0, s[10:11]
	s_mov_b32 m0, s30
	ds_read_b128 v[186:189], v156 offset:49152
	ds_read_b128 v[190:193], v156 offset:50176
	ds_read_b128 v[194:197], v156 offset:51200
	ds_read_b128 v[198:201], v156 offset:52224
	ds_read_b128 v[202:205], v156 offset:53248
	ds_read_b128 v[206:209], v156 offset:54272
	ds_read_b128 v[214:217], v156 offset:55296
	ds_read_b128 v[218:221], v156 offset:56320
	global_load_lds_dwordx4 v[210:211], off
	s_add_i32 m0, s30, 0x2000
	s_add_u32 s28, s28, 0x80080
	v_lshl_add_u64 v[210:211], v[222:223], 0, s[10:11]
	s_addc_u32 s29, s29, 0
	s_add_i32 s30, s53, s37
	global_load_lds_dwordx4 v[210:211], off
	v_lshl_add_u64 v[210:211], s[28:29], 0, v[132:133]
	s_mov_b32 m0, s30
	s_nop 0
	global_load_lds_dwordx4 v[210:211], off
	v_lshl_add_u64 v[210:211], s[28:29], 0, v[136:137]
	s_add_i32 m0, s30, 0x2000
	s_nop 0
	global_load_lds_dwordx4 v[210:211], off
	v_lshl_add_u64 v[210:211], v[224:225], 0, s[10:11]
	s_mov_b32 m0, s42
	s_nop 0
	global_load_lds_dwordx4 v[210:211], off
	v_lshl_add_u64 v[210:211], v[226:227], 0, s[10:11]
	s_mov_b32 m0, s43
	s_nop 0
	global_load_lds_dwordx4 v[210:211], off
	s_waitcnt vmcnt(8)
	s_waitcnt lgkmcnt(0)
	s_barrier
	s_setprio 1
	s_waitcnt lgkmcnt(0)
	v_mfma_f32_16x16x32_bf16 v[62:65], v[146:149], v[186:189], v[62:65]
	v_mfma_f32_16x16x32_bf16 v[58:61], v[162:165], v[186:189], v[58:61]
	v_mfma_f32_16x16x32_bf16 v[46:49], v[146:149], v[194:197], v[46:49]
	v_mfma_f32_16x16x32_bf16 v[42:45], v[162:165], v[194:197], v[42:45]
	v_mfma_f32_16x16x32_bf16 v[30:33], v[146:149], v[202:205], v[30:33]
	v_mfma_f32_16x16x32_bf16 v[26:29], v[162:165], v[202:205], v[26:29]
	v_mfma_f32_16x16x32_bf16 v[14:17], v[146:149], v[214:217], v[14:17]
	v_mfma_f32_16x16x32_bf16 v[10:13], v[162:165], v[214:217], v[10:13]
	v_mfma_f32_16x16x32_bf16 v[62:65], v[158:161], v[190:193], v[62:65]
	v_mfma_f32_16x16x32_bf16 v[58:61], v[166:169], v[190:193], v[58:61]
	v_mfma_f32_16x16x32_bf16 v[46:49], v[158:161], v[198:201], v[46:49]
	v_mfma_f32_16x16x32_bf16 v[42:45], v[166:169], v[198:201], v[42:45]
	v_mfma_f32_16x16x32_bf16 v[30:33], v[158:161], v[206:209], v[30:33]
	v_mfma_f32_16x16x32_bf16 v[26:29], v[166:169], v[206:209], v[26:29]
	v_mfma_f32_16x16x32_bf16 v[14:17], v[158:161], v[218:221], v[14:17]
	v_mfma_f32_16x16x32_bf16 v[10:13], v[166:169], v[218:221], v[10:13]
	s_setprio 0
	s_setprio 1
	v_mfma_f32_16x16x32_bf16 v[54:57], v[170:173], v[186:189], v[54:57]
	v_mfma_f32_16x16x32_bf16 v[50:53], v[178:181], v[186:189], v[50:53]
	v_mfma_f32_16x16x32_bf16 v[38:41], v[170:173], v[194:197], v[38:41]
	v_mfma_f32_16x16x32_bf16 v[34:37], v[178:181], v[194:197], v[34:37]
	v_mfma_f32_16x16x32_bf16 v[22:25], v[170:173], v[202:205], v[22:25]
	v_mfma_f32_16x16x32_bf16 v[18:21], v[178:181], v[202:205], v[18:21]
	v_mfma_f32_16x16x32_bf16 v[6:9], v[170:173], v[214:217], v[6:9]
	v_mfma_f32_16x16x32_bf16 v[2:5], v[178:181], v[214:217], v[2:5]
	v_mfma_f32_16x16x32_bf16 v[54:57], v[174:177], v[190:193], v[54:57]
	v_mfma_f32_16x16x32_bf16 v[50:53], v[182:185], v[190:193], v[50:53]
	v_mfma_f32_16x16x32_bf16 v[38:41], v[174:177], v[198:201], v[38:41]
	v_mfma_f32_16x16x32_bf16 v[34:37], v[182:185], v[198:201], v[34:37]
	v_mfma_f32_16x16x32_bf16 v[22:25], v[174:177], v[206:209], v[22:25]
	v_mfma_f32_16x16x32_bf16 v[18:21], v[182:185], v[206:209], v[18:21]
	v_mfma_f32_16x16x32_bf16 v[6:9], v[174:177], v[218:221], v[6:9]
	v_mfma_f32_16x16x32_bf16 v[2:5], v[182:185], v[218:221], v[2:5]
	s_setprio 0
	s_add_i32 s51, s51, 2
	s_add_u32 s26, s26, 0x100
	s_addc_u32 s27, s27, 0
	s_add_u32 s49, s49, 0x100
	s_addc_u32 s50, s50, 0
	s_cmp_gt_u32 s51, 29
	s_barrier
	s_cbranch_scc0 .LBB0_1517
	s_and_b64 vcc, exec, s[12:13]
	s_cbranch_vccz .LBB0_1520
	s_barrier

.LBB0_1624:
	ds_read_b128 v[146:149], v157
	ds_read_b128 v[150:153], v157 offset:1024
	ds_read_b128 v[162:165], v157 offset:2048
	ds_read_b128 v[166:169], v157 offset:3072
	ds_read_b128 v[170:173], v158
	ds_read_b128 v[174:177], v158 offset:1024
	ds_read_b128 v[178:181], v158 offset:2048
	ds_read_b128 v[182:185], v158 offset:3072
	s_add_u32 s34, s30, 0xfff80080
	s_addc_u32 s35, s31, -1
	s_cmp_eq_u32 s62, 28
	s_cselect_b32 s37, s25, s35
	s_cselect_b32 s36, s58, s34
	s_cselect_b32 s35, s23, s61
	s_cselect_b32 s34, s59, s60
	v_lshl_add_u64 v[210:211], s[30:31], 0, v[138:139]
	s_add_i32 m0, s43, 0xc000
	ds_read_b128 v[186:189], v159
	ds_read_b128 v[190:193], v159 offset:1024
	ds_read_b128 v[194:197], v159 offset:2048
	ds_read_b128 v[198:201], v159 offset:3072
	ds_read_b128 v[202:205], v159 offset:4096
	ds_read_b128 v[206:209], v159 offset:5120
	ds_read_b128 v[214:217], v159 offset:6144
	ds_read_b128 v[218:221], v159 offset:7168
	global_load_lds_dwordx4 v[210:211], off
	v_lshl_add_u64 v[210:211], s[30:31], 0, v[140:141]
	s_add_i32 m0, s43, 0xe000
	s_nop 0
	global_load_lds_dwordx4 v[210:211], off
	s_waitcnt vmcnt(8)
	s_waitcnt lgkmcnt(0)
	s_barrier
	s_setprio 1
	s_waitcnt lgkmcnt(0)
	v_mfma_f32_16x16x32_bf16 v[126:129], v[146:149], v[186:189], v[126:129]
	v_mfma_f32_16x16x32_bf16 v[122:125], v[162:165], v[186:189], v[122:125]
	v_mfma_f32_16x16x32_bf16 v[110:113], v[146:149], v[194:197], v[110:113]
	v_mfma_f32_16x16x32_bf16 v[106:109], v[162:165], v[194:197], v[106:109]
	v_mfma_f32_16x16x32_bf16 v[94:97], v[146:149], v[202:205], v[94:97]
	v_mfma_f32_16x16x32_bf16 v[90:93], v[162:165], v[202:205], v[90:93]
	v_mfma_f32_16x16x32_bf16 v[78:81], v[146:149], v[214:217], v[78:81]
	v_mfma_f32_16x16x32_bf16 v[74:77], v[162:165], v[214:217], v[74:77]
	v_mfma_f32_16x16x32_bf16 v[126:129], v[150:153], v[190:193], v[126:129]
	v_mfma_f32_16x16x32_bf16 v[122:125], v[166:169], v[190:193], v[122:125]
	v_mfma_f32_16x16x32_bf16 v[110:113], v[150:153], v[198:201], v[110:113]
	v_mfma_f32_16x16x32_bf16 v[106:109], v[166:169], v[198:201], v[106:109]
	v_mfma_f32_16x16x32_bf16 v[94:97], v[150:153], v[206:209], v[94:97]
	v_mfma_f32_16x16x32_bf16 v[90:93], v[166:169], v[206:209], v[90:93]
	v_mfma_f32_16x16x32_bf16 v[78:81], v[150:153], v[218:221], v[78:81]
	v_mfma_f32_16x16x32_bf16 v[74:77], v[166:169], v[218:221], v[74:77]
	s_setprio 0
	s_setprio 1
	v_mfma_f32_16x16x32_bf16 v[118:121], v[170:173], v[186:189], v[118:121]
	v_mfma_f32_16x16x32_bf16 v[114:117], v[178:181], v[186:189], v[114:117]
	v_mfma_f32_16x16x32_bf16 v[102:105], v[170:173], v[194:197], v[102:105]
	v_mfma_f32_16x16x32_bf16 v[98:101], v[178:181], v[194:197], v[98:101]
	v_mfma_f32_16x16x32_bf16 v[86:89], v[170:173], v[202:205], v[86:89]
	v_mfma_f32_16x16x32_bf16 v[82:85], v[178:181], v[202:205], v[82:85]
	v_mfma_f32_16x16x32_bf16 v[70:73], v[170:173], v[214:217], v[70:73]
	v_mfma_f32_16x16x32_bf16 v[66:69], v[178:181], v[214:217], v[66:69]
	v_mfma_f32_16x16x32_bf16 v[118:121], v[174:177], v[190:193], v[118:121]
	v_mfma_f32_16x16x32_bf16 v[114:117], v[182:185], v[190:193], v[114:117]
	v_mfma_f32_16x16x32_bf16 v[102:105], v[174:177], v[198:201], v[102:105]
	v_mfma_f32_16x16x32_bf16 v[98:101], v[182:185], v[198:201], v[98:101]
	v_mfma_f32_16x16x32_bf16 v[86:89], v[174:177], v[206:209], v[86:89]
	v_mfma_f32_16x16x32_bf16 v[82:85], v[182:185], v[206:209], v[82:85]
	v_mfma_f32_16x16x32_bf16 v[70:73], v[174:177], v[218:221], v[70:73]
	v_mfma_f32_16x16x32_bf16 v[66:69], v[182:185], v[218:221], v[66:69]
	s_setprio 0
	s_barrier
	s_add_i32 s63, s51, s42
	v_lshl_add_u64 v[210:211], s[34:35], 0, v[132:133]
	s_mov_b32 m0, s63
	ds_read_b128 v[186:189], v159 offset:16384
	ds_read_b128 v[190:193], v159 offset:17408
	ds_read_b128 v[194:197], v159 offset:18432
	ds_read_b128 v[198:201], v159 offset:19456
	ds_read_b128 v[202:205], v159 offset:20480
	ds_read_b128 v[206:209], v159 offset:21504
	ds_read_b128 v[214:217], v159 offset:22528
	ds_read_b128 v[218:221], v159 offset:23552
	global_load_lds_dwordx4 v[210:211], off
	s_add_i32 m0, s63, 0x2000
	s_add_u32 s64, s34, 0x80000
	v_lshl_add_u64 v[222:223], s[34:35], 0, v[136:137]
	s_addc_u32 s65, s35, 0
	s_add_i32 s63, s52, s42
	global_load_lds_dwordx4 v[222:223], off
	v_lshl_add_u64 v[224:225], s[64:65], 0, v[132:133]
	s_mov_b32 m0, s63
	v_lshl_add_u64 v[226:227], s[36:37], 0, v[134:135]
	global_load_lds_dwordx4 v[224:225], off
	v_lshl_add_u64 v[224:225], s[64:65], 0, v[136:137]
	s_add_i32 m0, s63, 0x2000
	s_nop 0
	global_load_lds_dwordx4 v[224:225], off
	v_lshl_add_u64 v[224:225], s[36:37], 0, v[130:131]
	s_mov_b32 m0, s43
	s_nop 0
	global_load_lds_dwordx4 v[224:225], off
	s_mov_b32 m0, s44
	s_nop 0
	global_load_lds_dwordx4 v[226:227], off
	s_waitcnt vmcnt(8)
	s_waitcnt lgkmcnt(0)
	s_barrier
	s_setprio 1
	s_waitcnt lgkmcnt(0)
	v_mfma_f32_16x16x32_bf16 v[62:65], v[146:149], v[186:189], v[62:65]
	v_mfma_f32_16x16x32_bf16 v[58:61], v[162:165], v[186:189], v[58:61]
	v_mfma_f32_16x16x32_bf16 v[46:49], v[146:149], v[194:197], v[46:49]
	v_mfma_f32_16x16x32_bf16 v[42:45], v[162:165], v[194:197], v[42:45]
	v_mfma_f32_16x16x32_bf16 v[30:33], v[146:149], v[202:205], v[30:33]
	v_mfma_f32_16x16x32_bf16 v[26:29], v[162:165], v[202:205], v[26:29]
	v_mfma_f32_16x16x32_bf16 v[14:17], v[146:149], v[214:217], v[14:17]
	v_mfma_f32_16x16x32_bf16 v[10:13], v[162:165], v[214:217], v[10:13]
	v_mfma_f32_16x16x32_bf16 v[62:65], v[150:153], v[190:193], v[62:65]
	v_mfma_f32_16x16x32_bf16 v[58:61], v[166:169], v[190:193], v[58:61]
	v_mfma_f32_16x16x32_bf16 v[46:49], v[150:153], v[198:201], v[46:49]
	v_mfma_f32_16x16x32_bf16 v[42:45], v[166:169], v[198:201], v[42:45]
	v_mfma_f32_16x16x32_bf16 v[30:33], v[150:153], v[206:209], v[30:33]
	v_mfma_f32_16x16x32_bf16 v[26:29], v[166:169], v[206:209], v[26:29]
	v_mfma_f32_16x16x32_bf16 v[14:17], v[150:153], v[218:221], v[14:17]
	v_mfma_f32_16x16x32_bf16 v[10:13], v[166:169], v[218:221], v[10:13]
	s_setprio 0
	s_setprio 1
	v_mfma_f32_16x16x32_bf16 v[54:57], v[170:173], v[186:189], v[54:57]
	v_mfma_f32_16x16x32_bf16 v[50:53], v[178:181], v[186:189], v[50:53]
	v_mfma_f32_16x16x32_bf16 v[38:41], v[170:173], v[194:197], v[38:41]
	v_mfma_f32_16x16x32_bf16 v[34:37], v[178:181], v[194:197], v[34:37]
	v_mfma_f32_16x16x32_bf16 v[22:25], v[170:173], v[202:205], v[22:25]
	v_mfma_f32_16x16x32_bf16 v[18:21], v[178:181], v[202:205], v[18:21]
	v_mfma_f32_16x16x32_bf16 v[6:9], v[170:173], v[214:217], v[6:9]
	v_mfma_f32_16x16x32_bf16 v[2:5], v[178:181], v[214:217], v[2:5]
	v_mfma_f32_16x16x32_bf16 v[54:57], v[174:177], v[190:193], v[54:57]
	v_mfma_f32_16x16x32_bf16 v[50:53], v[182:185], v[190:193], v[50:53]
	v_mfma_f32_16x16x32_bf16 v[38:41], v[174:177], v[198:201], v[38:41]
	v_mfma_f32_16x16x32_bf16 v[34:37], v[182:185], v[198:201], v[34:37]
	v_mfma_f32_16x16x32_bf16 v[22:25], v[174:177], v[206:209], v[22:25]
	v_mfma_f32_16x16x32_bf16 v[18:21], v[182:185], v[206:209], v[18:21]
	v_mfma_f32_16x16x32_bf16 v[6:9], v[174:177], v[218:221], v[6:9]
	v_mfma_f32_16x16x32_bf16 v[2:5], v[182:185], v[218:221], v[2:5]
	s_setprio 0
	s_barrier
	s_add_i32 s63, 0, 0x18000
	v_add_u32_e32 v161, s63, v155
	s_add_i32 s64, 0, 0x1c000
	ds_read_b128 v[146:149], v161
	ds_read_b128 v[150:153], v161 offset:1024
	ds_read_b128 v[162:165], v161 offset:2048
	ds_read_b128 v[166:169], v161 offset:3072
	v_add_u32_e32 v161, s64, v155
	ds_read_b128 v[170:173], v161
	ds_read_b128 v[174:177], v161 offset:1024
	ds_read_b128 v[178:181], v161 offset:2048
	ds_read_b128 v[182:185], v161 offset:3072
	s_add_u32 s36, s36, 0x80000
	s_addc_u32 s37, s37, 0
	s_mov_b32 m0, s45
	v_lshl_add_u64 v[228:229], s[36:37], 0, v[130:131]
	ds_read_b128 v[186:189], v159 offset:32768
	ds_read_b128 v[190:193], v159 offset:33792
	ds_read_b128 v[194:197], v159 offset:34816
	ds_read_b128 v[198:201], v159 offset:35840
	ds_read_b128 v[202:205], v159 offset:36864
	ds_read_b128 v[206:209], v159 offset:37888
	ds_read_b128 v[214:217], v159 offset:38912
	ds_read_b128 v[218:221], v159 offset:39936
	global_load_lds_dwordx4 v[228:229], off
	v_lshl_add_u64 v[228:229], s[36:37], 0, v[134:135]
	s_mov_b32 m0, s46
	s_nop 0
	global_load_lds_dwordx4 v[228:229], off
	s_waitcnt vmcnt(8)
	s_waitcnt lgkmcnt(0)
	s_barrier
	s_setprio 1
	s_waitcnt lgkmcnt(0)
	v_mfma_f32_16x16x32_bf16 v[126:129], v[146:149], v[186:189], v[126:129]
	v_mfma_f32_16x16x32_bf16 v[122:125], v[162:165], v[186:189], v[122:125]
	v_mfma_f32_16x16x32_bf16 v[110:113], v[146:149], v[194:197], v[110:113]
	v_mfma_f32_16x16x32_bf16 v[106:109], v[162:165], v[194:197], v[106:109]
	v_mfma_f32_16x16x32_bf16 v[94:97], v[146:149], v[202:205], v[94:97]
	v_mfma_f32_16x16x32_bf16 v[90:93], v[162:165], v[202:205], v[90:93]
	v_mfma_f32_16x16x32_bf16 v[78:81], v[146:149], v[214:217], v[78:81]
	v_mfma_f32_16x16x32_bf16 v[74:77], v[162:165], v[214:217], v[74:77]
	v_mfma_f32_16x16x32_bf16 v[126:129], v[150:153], v[190:193], v[126:129]
	v_mfma_f32_16x16x32_bf16 v[122:125], v[166:169], v[190:193], v[122:125]
	v_mfma_f32_16x16x32_bf16 v[110:113], v[150:153], v[198:201], v[110:113]
	v_mfma_f32_16x16x32_bf16 v[106:109], v[166:169], v[198:201], v[106:109]
	v_mfma_f32_16x16x32_bf16 v[94:97], v[150:153], v[206:209], v[94:97]
	v_mfma_f32_16x16x32_bf16 v[90:93], v[166:169], v[206:209], v[90:93]
	v_mfma_f32_16x16x32_bf16 v[78:81], v[150:153], v[218:221], v[78:81]
	v_mfma_f32_16x16x32_bf16 v[74:77], v[166:169], v[218:221], v[74:77]
	s_setprio 0
	s_setprio 1
	v_mfma_f32_16x16x32_bf16 v[118:121], v[170:173], v[186:189], v[118:121]
	v_mfma_f32_16x16x32_bf16 v[114:117], v[178:181], v[186:189], v[114:117]
	v_mfma_f32_16x16x32_bf16 v[102:105], v[170:173], v[194:197], v[102:105]
	v_mfma_f32_16x16x32_bf16 v[98:101], v[178:181], v[194:197], v[98:101]
	v_mfma_f32_16x16x32_bf16 v[86:89], v[170:173], v[202:205], v[86:89]
	v_mfma_f32_16x16x32_bf16 v[82:85], v[178:181], v[202:205], v[82:85]
	v_mfma_f32_16x16x32_bf16 v[70:73], v[170:173], v[214:217], v[70:73]
	v_mfma_f32_16x16x32_bf16 v[66:69], v[178:181], v[214:217], v[66:69]
	v_mfma_f32_16x16x32_bf16 v[118:121], v[174:177], v[190:193], v[118:121]
	v_mfma_f32_16x16x32_bf16 v[114:117], v[182:185], v[190:193], v[114:117]
	v_mfma_f32_16x16x32_bf16 v[102:105], v[174:177], v[198:201], v[102:105]
	v_mfma_f32_16x16x32_bf16 v[98:101], v[182:185], v[198:201], v[98:101]
	v_mfma_f32_16x16x32_bf16 v[86:89], v[174:177], v[206:209], v[86:89]
	v_mfma_f32_16x16x32_bf16 v[82:85], v[182:185], v[206:209], v[82:85]
	v_mfma_f32_16x16x32_bf16 v[70:73], v[174:177], v[218:221], v[70:73]
	v_mfma_f32_16x16x32_bf16 v[66:69], v[182:185], v[218:221], v[66:69]
	s_setprio 0
	s_barrier
	s_add_i32 s36, s63, s42
	v_lshl_add_u64 v[210:211], v[210:211], 0, s[10:11]
	s_mov_b32 m0, s36
	ds_read_b128 v[186:189], v159 offset:49152
	ds_read_b128 v[190:193], v159 offset:50176
	ds_read_b128 v[194:197], v159 offset:51200
	ds_read_b128 v[198:201], v159 offset:52224
	ds_read_b128 v[202:205], v159 offset:53248
	ds_read_b128 v[206:209], v159 offset:54272
	ds_read_b128 v[214:217], v159 offset:55296
	ds_read_b128 v[218:221], v159 offset:56320
	global_load_lds_dwordx4 v[210:211], off
	s_add_i32 m0, s36, 0x2000
	s_add_u32 s34, s34, 0x80080
	v_lshl_add_u64 v[210:211], v[222:223], 0, s[10:11]
	s_addc_u32 s35, s35, 0
	s_add_i32 s36, s64, s42
	global_load_lds_dwordx4 v[210:211], off
	v_lshl_add_u64 v[210:211], s[34:35], 0, v[132:133]
	s_mov_b32 m0, s36
	s_nop 0
	global_load_lds_dwordx4 v[210:211], off
	v_lshl_add_u64 v[210:211], s[34:35], 0, v[136:137]
	s_add_i32 m0, s36, 0x2000
	s_nop 0
	global_load_lds_dwordx4 v[210:211], off
	v_lshl_add_u64 v[210:211], v[224:225], 0, s[10:11]
	s_mov_b32 m0, s48
	s_nop 0
	global_load_lds_dwordx4 v[210:211], off
	v_lshl_add_u64 v[210:211], v[226:227], 0, s[10:11]
	s_mov_b32 m0, s49
	s_nop 0
	global_load_lds_dwordx4 v[210:211], off
	s_waitcnt vmcnt(8)
	s_waitcnt lgkmcnt(0)
	s_barrier
	s_setprio 1
	s_waitcnt lgkmcnt(0)
	v_mfma_f32_16x16x32_bf16 v[62:65], v[146:149], v[186:189], v[62:65]
	v_mfma_f32_16x16x32_bf16 v[58:61], v[162:165], v[186:189], v[58:61]
	v_mfma_f32_16x16x32_bf16 v[46:49], v[146:149], v[194:197], v[46:49]
	v_mfma_f32_16x16x32_bf16 v[42:45], v[162:165], v[194:197], v[42:45]
	v_mfma_f32_16x16x32_bf16 v[30:33], v[146:149], v[202:205], v[30:33]
	v_mfma_f32_16x16x32_bf16 v[26:29], v[162:165], v[202:205], v[26:29]
	v_mfma_f32_16x16x32_bf16 v[14:17], v[146:149], v[214:217], v[14:17]
	v_mfma_f32_16x16x32_bf16 v[10:13], v[162:165], v[214:217], v[10:13]
	v_mfma_f32_16x16x32_bf16 v[62:65], v[150:153], v[190:193], v[62:65]
	v_mfma_f32_16x16x32_bf16 v[58:61], v[166:169], v[190:193], v[58:61]
	v_mfma_f32_16x16x32_bf16 v[46:49], v[150:153], v[198:201], v[46:49]
	v_mfma_f32_16x16x32_bf16 v[42:45], v[166:169], v[198:201], v[42:45]
	v_mfma_f32_16x16x32_bf16 v[30:33], v[150:153], v[206:209], v[30:33]
	v_mfma_f32_16x16x32_bf16 v[26:29], v[166:169], v[206:209], v[26:29]
	v_mfma_f32_16x16x32_bf16 v[14:17], v[150:153], v[218:221], v[14:17]
	v_mfma_f32_16x16x32_bf16 v[10:13], v[166:169], v[218:221], v[10:13]
	s_setprio 0
	s_setprio 1
	v_mfma_f32_16x16x32_bf16 v[54:57], v[170:173], v[186:189], v[54:57]
	v_mfma_f32_16x16x32_bf16 v[50:53], v[178:181], v[186:189], v[50:53]
	v_mfma_f32_16x16x32_bf16 v[38:41], v[170:173], v[194:197], v[38:41]
	v_mfma_f32_16x16x32_bf16 v[34:37], v[178:181], v[194:197], v[34:37]
	v_mfma_f32_16x16x32_bf16 v[22:25], v[170:173], v[202:205], v[22:25]
	v_mfma_f32_16x16x32_bf16 v[18:21], v[178:181], v[202:205], v[18:21]
	v_mfma_f32_16x16x32_bf16 v[6:9], v[170:173], v[214:217], v[6:9]
	v_mfma_f32_16x16x32_bf16 v[2:5], v[178:181], v[214:217], v[2:5]
	v_mfma_f32_16x16x32_bf16 v[54:57], v[174:177], v[190:193], v[54:57]
	v_mfma_f32_16x16x32_bf16 v[50:53], v[182:185], v[190:193], v[50:53]
	v_mfma_f32_16x16x32_bf16 v[38:41], v[174:177], v[198:201], v[38:41]
	v_mfma_f32_16x16x32_bf16 v[34:37], v[182:185], v[198:201], v[34:37]
	v_mfma_f32_16x16x32_bf16 v[22:25], v[174:177], v[206:209], v[22:25]
	v_mfma_f32_16x16x32_bf16 v[18:21], v[182:185], v[206:209], v[18:21]
	v_mfma_f32_16x16x32_bf16 v[6:9], v[174:177], v[218:221], v[6:9]
	v_mfma_f32_16x16x32_bf16 v[2:5], v[182:185], v[218:221], v[2:5]
	s_setprio 0
	s_add_i32 s62, s62, 2
	s_add_u32 s30, s30, 0x100
	s_addc_u32 s31, s31, 0
	s_add_u32 s60, s60, 0x100
	s_addc_u32 s61, s61, 0
	s_cmp_gt_u32 s62, 29
	s_barrier
	s_cbranch_scc0 .LBB0_1624
	s_and_b64 vcc, exec, s[12:13]
	s_cbranch_vccz .LBB0_1627
	s_barrier

.LBB0_1714:
	ds_read_b128 v[146:149], v155
	ds_read_b128 v[158:161], v155 offset:1024
	ds_read_b128 v[162:165], v155 offset:2048
	ds_read_b128 v[166:169], v155 offset:3072
	ds_read_b128 v[170:173], v156
	ds_read_b128 v[174:177], v156 offset:1024
	ds_read_b128 v[178:181], v156 offset:2048
	ds_read_b128 v[182:185], v156 offset:3072
	s_add_u32 s30, s28, 0xffe00080
	s_addc_u32 s31, s29, -1
	s_cmpk_eq_i32 s59, 0x7c
	s_cselect_b32 s35, s21, s31
	s_cselect_b32 s34, s55, s30
	s_cselect_b32 s31, s19, s58
	s_cselect_b32 s30, s56, s57
	v_lshl_add_u64 v[150:151], s[28:29], 0, v[138:139]
	s_add_i32 m0, s27, 0xc000
	ds_read_b128 v[186:189], v157
	ds_read_b128 v[190:193], v157 offset:1024
	ds_read_b128 v[194:197], v157 offset:2048
	ds_read_b128 v[198:201], v157 offset:3072
	ds_read_b128 v[202:205], v157 offset:4096
	ds_read_b128 v[206:209], v157 offset:5120
	ds_read_b128 v[214:217], v157 offset:6144
	ds_read_b128 v[218:221], v157 offset:7168
	global_load_lds_dwordx4 v[150:151], off
	v_lshl_add_u64 v[150:151], s[28:29], 0, v[140:141]
	s_add_i32 m0, s27, 0xe000
	s_nop 0
	global_load_lds_dwordx4 v[150:151], off
	s_waitcnt vmcnt(8)
	s_waitcnt lgkmcnt(0)
	s_barrier
	s_setprio 1
	s_waitcnt lgkmcnt(0)
	v_mfma_f32_16x16x32_bf16 v[126:129], v[146:149], v[186:189], v[126:129]
	v_mfma_f32_16x16x32_bf16 v[122:125], v[162:165], v[186:189], v[122:125]
	v_mfma_f32_16x16x32_bf16 v[118:121], v[146:149], v[194:197], v[118:121]
	v_mfma_f32_16x16x32_bf16 v[106:109], v[162:165], v[194:197], v[106:109]
	v_mfma_f32_16x16x32_bf16 v[102:105], v[146:149], v[202:205], v[102:105]
	v_mfma_f32_16x16x32_bf16 v[90:93], v[162:165], v[202:205], v[90:93]
	v_mfma_f32_16x16x32_bf16 v[86:89], v[146:149], v[214:217], v[86:89]
	v_mfma_f32_16x16x32_bf16 v[74:77], v[162:165], v[214:217], v[74:77]
	v_mfma_f32_16x16x32_bf16 v[126:129], v[158:161], v[190:193], v[126:129]
	v_mfma_f32_16x16x32_bf16 v[122:125], v[166:169], v[190:193], v[122:125]
	v_mfma_f32_16x16x32_bf16 v[118:121], v[158:161], v[198:201], v[118:121]
	v_mfma_f32_16x16x32_bf16 v[106:109], v[166:169], v[198:201], v[106:109]
	v_mfma_f32_16x16x32_bf16 v[102:105], v[158:161], v[206:209], v[102:105]
	v_mfma_f32_16x16x32_bf16 v[90:93], v[166:169], v[206:209], v[90:93]
	v_mfma_f32_16x16x32_bf16 v[86:89], v[158:161], v[218:221], v[86:89]
	v_mfma_f32_16x16x32_bf16 v[74:77], v[166:169], v[218:221], v[74:77]
	s_setprio 0
	s_setprio 1
	v_mfma_f32_16x16x32_bf16 v[114:117], v[170:173], v[186:189], v[114:117]
	v_mfma_f32_16x16x32_bf16 v[110:113], v[178:181], v[186:189], v[110:113]
	v_mfma_f32_16x16x32_bf16 v[98:101], v[170:173], v[194:197], v[98:101]
	v_mfma_f32_16x16x32_bf16 v[94:97], v[178:181], v[194:197], v[94:97]
	v_mfma_f32_16x16x32_bf16 v[82:85], v[170:173], v[202:205], v[82:85]
	v_mfma_f32_16x16x32_bf16 v[78:81], v[178:181], v[202:205], v[78:81]
	v_mfma_f32_16x16x32_bf16 v[70:73], v[170:173], v[214:217], v[70:73]
	v_mfma_f32_16x16x32_bf16 v[66:69], v[178:181], v[214:217], v[66:69]
	v_mfma_f32_16x16x32_bf16 v[114:117], v[174:177], v[190:193], v[114:117]
	v_mfma_f32_16x16x32_bf16 v[110:113], v[182:185], v[190:193], v[110:113]
	v_mfma_f32_16x16x32_bf16 v[98:101], v[174:177], v[198:201], v[98:101]
	v_mfma_f32_16x16x32_bf16 v[94:97], v[182:185], v[198:201], v[94:97]
	v_mfma_f32_16x16x32_bf16 v[82:85], v[174:177], v[206:209], v[82:85]
	v_mfma_f32_16x16x32_bf16 v[78:81], v[182:185], v[206:209], v[78:81]
	v_mfma_f32_16x16x32_bf16 v[70:73], v[174:177], v[218:221], v[70:73]
	v_mfma_f32_16x16x32_bf16 v[66:69], v[182:185], v[218:221], v[66:69]
	s_setprio 0
	s_barrier
	s_add_i32 s60, s48, s40
	v_lshl_add_u64 v[150:151], s[30:31], 0, v[132:133]
	s_mov_b32 m0, s60
	ds_read_b128 v[186:189], v157 offset:16384
	ds_read_b128 v[190:193], v157 offset:17408
	ds_read_b128 v[194:197], v157 offset:18432
	ds_read_b128 v[198:201], v157 offset:19456
	ds_read_b128 v[202:205], v157 offset:20480
	ds_read_b128 v[206:209], v157 offset:21504
	ds_read_b128 v[214:217], v157 offset:22528
	ds_read_b128 v[218:221], v157 offset:23552
	global_load_lds_dwordx4 v[150:151], off
	s_add_i32 m0, s60, 0x2000
	s_add_u32 s60, s30, 0x200000
	v_lshl_add_u64 v[210:211], s[30:31], 0, v[136:137]
	s_addc_u32 s61, s31, 0
	s_add_i32 s62, s49, s40
	global_load_lds_dwordx4 v[210:211], off
	v_lshl_add_u64 v[222:223], s[60:61], 0, v[132:133]
	s_mov_b32 m0, s62
	v_lshl_add_u64 v[224:225], s[34:35], 0, v[134:135]
	global_load_lds_dwordx4 v[222:223], off
	v_lshl_add_u64 v[222:223], s[60:61], 0, v[136:137]
	s_add_i32 m0, s62, 0x2000
	s_nop 0
	global_load_lds_dwordx4 v[222:223], off
	v_lshl_add_u64 v[222:223], s[34:35], 0, v[130:131]
	s_mov_b32 m0, s27
	s_nop 0
	global_load_lds_dwordx4 v[222:223], off
	s_mov_b32 m0, s41
	s_nop 0
	global_load_lds_dwordx4 v[224:225], off
	s_waitcnt vmcnt(8)
	s_waitcnt lgkmcnt(0)
	s_barrier
	s_setprio 1
	s_waitcnt lgkmcnt(0)
	v_mfma_f32_16x16x32_bf16 v[62:65], v[146:149], v[186:189], v[62:65]
	v_mfma_f32_16x16x32_bf16 v[58:61], v[162:165], v[186:189], v[58:61]
	v_mfma_f32_16x16x32_bf16 v[50:53], v[146:149], v[194:197], v[50:53]
	v_mfma_f32_16x16x32_bf16 v[42:45], v[162:165], v[194:197], v[42:45]
	v_mfma_f32_16x16x32_bf16 v[34:37], v[146:149], v[202:205], v[34:37]
	v_mfma_f32_16x16x32_bf16 v[26:29], v[162:165], v[202:205], v[26:29]
	v_mfma_f32_16x16x32_bf16 v[18:21], v[146:149], v[214:217], v[18:21]
	v_mfma_f32_16x16x32_bf16 v[10:13], v[162:165], v[214:217], v[10:13]
	v_mfma_f32_16x16x32_bf16 v[62:65], v[158:161], v[190:193], v[62:65]
	v_mfma_f32_16x16x32_bf16 v[58:61], v[166:169], v[190:193], v[58:61]
	v_mfma_f32_16x16x32_bf16 v[50:53], v[158:161], v[198:201], v[50:53]
	v_mfma_f32_16x16x32_bf16 v[42:45], v[166:169], v[198:201], v[42:45]
	v_mfma_f32_16x16x32_bf16 v[34:37], v[158:161], v[206:209], v[34:37]
	v_mfma_f32_16x16x32_bf16 v[26:29], v[166:169], v[206:209], v[26:29]
	v_mfma_f32_16x16x32_bf16 v[18:21], v[158:161], v[218:221], v[18:21]
	v_mfma_f32_16x16x32_bf16 v[10:13], v[166:169], v[218:221], v[10:13]
	s_setprio 0
	s_setprio 1
	v_mfma_f32_16x16x32_bf16 v[54:57], v[170:173], v[186:189], v[54:57]
	v_mfma_f32_16x16x32_bf16 v[46:49], v[178:181], v[186:189], v[46:49]
	v_mfma_f32_16x16x32_bf16 v[38:41], v[170:173], v[194:197], v[38:41]
	v_mfma_f32_16x16x32_bf16 v[30:33], v[178:181], v[194:197], v[30:33]
	v_mfma_f32_16x16x32_bf16 v[22:25], v[170:173], v[202:205], v[22:25]
	v_mfma_f32_16x16x32_bf16 v[14:17], v[178:181], v[202:205], v[14:17]
	v_mfma_f32_16x16x32_bf16 v[6:9], v[170:173], v[214:217], v[6:9]
	v_mfma_f32_16x16x32_bf16 v[2:5], v[178:181], v[214:217], v[2:5]
	v_mfma_f32_16x16x32_bf16 v[54:57], v[174:177], v[190:193], v[54:57]
	v_mfma_f32_16x16x32_bf16 v[46:49], v[182:185], v[190:193], v[46:49]
	v_mfma_f32_16x16x32_bf16 v[38:41], v[174:177], v[198:201], v[38:41]
	v_mfma_f32_16x16x32_bf16 v[30:33], v[182:185], v[198:201], v[30:33]
	v_mfma_f32_16x16x32_bf16 v[22:25], v[174:177], v[206:209], v[22:25]
	v_mfma_f32_16x16x32_bf16 v[14:17], v[182:185], v[206:209], v[14:17]
	v_mfma_f32_16x16x32_bf16 v[6:9], v[174:177], v[218:221], v[6:9]
	v_mfma_f32_16x16x32_bf16 v[2:5], v[182:185], v[218:221], v[2:5]
	s_setprio 0
	s_barrier
	s_add_i32 s60, 0, 0x18000
	s_add_i32 s61, 0, 0x1c000
	v_add_u32_e32 v166, s60, v153
	v_add_u32_e32 v182, s61, v153
	ds_read_b128 v[146:149], v166
	ds_read_b128 v[158:161], v166 offset:1024
	ds_read_b128 v[162:165], v166 offset:2048
	ds_read_b128 v[166:169], v166 offset:3072
	ds_read_b128 v[170:173], v182
	ds_read_b128 v[174:177], v182 offset:1024
	ds_read_b128 v[178:181], v182 offset:2048
	ds_read_b128 v[182:185], v182 offset:3072
	s_add_u32 s34, s34, 0x200000
	s_addc_u32 s35, s35, 0
	s_mov_b32 m0, s42
	v_lshl_add_u64 v[226:227], s[34:35], 0, v[130:131]
	ds_read_b128 v[186:189], v157 offset:32768
	ds_read_b128 v[190:193], v157 offset:33792
	ds_read_b128 v[194:197], v157 offset:34816
	ds_read_b128 v[198:201], v157 offset:35840
	ds_read_b128 v[202:205], v157 offset:36864
	ds_read_b128 v[206:209], v157 offset:37888
	ds_read_b128 v[214:217], v157 offset:38912
	ds_read_b128 v[218:221], v157 offset:39936
	global_load_lds_dwordx4 v[226:227], off
	v_lshl_add_u64 v[226:227], s[34:35], 0, v[134:135]
	s_mov_b32 m0, s43
	s_nop 0
	global_load_lds_dwordx4 v[226:227], off
	s_waitcnt vmcnt(8)
	s_waitcnt lgkmcnt(0)
	s_barrier
	s_setprio 1
	s_waitcnt lgkmcnt(0)
	v_mfma_f32_16x16x32_bf16 v[126:129], v[146:149], v[186:189], v[126:129]
	v_mfma_f32_16x16x32_bf16 v[122:125], v[162:165], v[186:189], v[122:125]
	v_mfma_f32_16x16x32_bf16 v[118:121], v[146:149], v[194:197], v[118:121]
	v_mfma_f32_16x16x32_bf16 v[106:109], v[162:165], v[194:197], v[106:109]
	v_mfma_f32_16x16x32_bf16 v[102:105], v[146:149], v[202:205], v[102:105]
	v_mfma_f32_16x16x32_bf16 v[90:93], v[162:165], v[202:205], v[90:93]
	v_mfma_f32_16x16x32_bf16 v[86:89], v[146:149], v[214:217], v[86:89]
	v_mfma_f32_16x16x32_bf16 v[74:77], v[162:165], v[214:217], v[74:77]
	v_mfma_f32_16x16x32_bf16 v[126:129], v[158:161], v[190:193], v[126:129]
	v_mfma_f32_16x16x32_bf16 v[122:125], v[166:169], v[190:193], v[122:125]
	v_mfma_f32_16x16x32_bf16 v[118:121], v[158:161], v[198:201], v[118:121]
	v_mfma_f32_16x16x32_bf16 v[106:109], v[166:169], v[198:201], v[106:109]
	v_mfma_f32_16x16x32_bf16 v[102:105], v[158:161], v[206:209], v[102:105]
	v_mfma_f32_16x16x32_bf16 v[90:93], v[166:169], v[206:209], v[90:93]
	v_mfma_f32_16x16x32_bf16 v[86:89], v[158:161], v[218:221], v[86:89]
	v_mfma_f32_16x16x32_bf16 v[74:77], v[166:169], v[218:221], v[74:77]
	s_setprio 0
	s_setprio 1
	v_mfma_f32_16x16x32_bf16 v[114:117], v[170:173], v[186:189], v[114:117]
	v_mfma_f32_16x16x32_bf16 v[110:113], v[178:181], v[186:189], v[110:113]
	v_mfma_f32_16x16x32_bf16 v[98:101], v[170:173], v[194:197], v[98:101]
	v_mfma_f32_16x16x32_bf16 v[94:97], v[178:181], v[194:197], v[94:97]
	v_mfma_f32_16x16x32_bf16 v[82:85], v[170:173], v[202:205], v[82:85]
	v_mfma_f32_16x16x32_bf16 v[78:81], v[178:181], v[202:205], v[78:81]
	v_mfma_f32_16x16x32_bf16 v[70:73], v[170:173], v[214:217], v[70:73]
	v_mfma_f32_16x16x32_bf16 v[66:69], v[178:181], v[214:217], v[66:69]
	v_mfma_f32_16x16x32_bf16 v[114:117], v[174:177], v[190:193], v[114:117]
	v_mfma_f32_16x16x32_bf16 v[110:113], v[182:185], v[190:193], v[110:113]
	v_mfma_f32_16x16x32_bf16 v[98:101], v[174:177], v[198:201], v[98:101]
	v_mfma_f32_16x16x32_bf16 v[94:97], v[182:185], v[198:201], v[94:97]
	v_mfma_f32_16x16x32_bf16 v[82:85], v[174:177], v[206:209], v[82:85]
	v_mfma_f32_16x16x32_bf16 v[78:81], v[182:185], v[206:209], v[78:81]
	v_mfma_f32_16x16x32_bf16 v[70:73], v[174:177], v[218:221], v[70:73]
	v_mfma_f32_16x16x32_bf16 v[66:69], v[182:185], v[218:221], v[66:69]
	s_setprio 0
	s_barrier
	s_add_i32 s34, s60, s40
	v_lshl_add_u64 v[150:151], v[150:151], 0, s[6:7]
	s_mov_b32 m0, s34
	ds_read_b128 v[186:189], v157 offset:49152
	ds_read_b128 v[190:193], v157 offset:50176
	ds_read_b128 v[194:197], v157 offset:51200
	ds_read_b128 v[198:201], v157 offset:52224
	ds_read_b128 v[202:205], v157 offset:53248
	ds_read_b128 v[206:209], v157 offset:54272
	ds_read_b128 v[214:217], v157 offset:55296
	ds_read_b128 v[218:221], v157 offset:56320
	global_load_lds_dwordx4 v[150:151], off
	s_add_i32 m0, s34, 0x2000
	s_add_u32 s30, s30, 0x200080
	v_lshl_add_u64 v[150:151], v[210:211], 0, s[6:7]
	s_addc_u32 s31, s31, 0
	s_add_i32 s34, s61, s40
	global_load_lds_dwordx4 v[150:151], off
	v_lshl_add_u64 v[150:151], s[30:31], 0, v[132:133]
	s_mov_b32 m0, s34
	s_nop 0
	global_load_lds_dwordx4 v[150:151], off
	v_lshl_add_u64 v[150:151], s[30:31], 0, v[136:137]
	s_add_i32 m0, s34, 0x2000
	s_nop 0
	global_load_lds_dwordx4 v[150:151], off
	v_lshl_add_u64 v[150:151], v[222:223], 0, s[6:7]
	s_mov_b32 m0, s45
	s_nop 0
	global_load_lds_dwordx4 v[150:151], off
	v_lshl_add_u64 v[150:151], v[224:225], 0, s[6:7]
	s_mov_b32 m0, s46
	s_nop 0
	global_load_lds_dwordx4 v[150:151], off
	s_waitcnt vmcnt(8)
	s_waitcnt lgkmcnt(0)
	s_barrier
	s_setprio 1
	s_waitcnt lgkmcnt(0)
	v_mfma_f32_16x16x32_bf16 v[62:65], v[146:149], v[186:189], v[62:65]
	v_mfma_f32_16x16x32_bf16 v[58:61], v[162:165], v[186:189], v[58:61]
	v_mfma_f32_16x16x32_bf16 v[50:53], v[146:149], v[194:197], v[50:53]
	v_mfma_f32_16x16x32_bf16 v[42:45], v[162:165], v[194:197], v[42:45]
	v_mfma_f32_16x16x32_bf16 v[34:37], v[146:149], v[202:205], v[34:37]
	v_mfma_f32_16x16x32_bf16 v[26:29], v[162:165], v[202:205], v[26:29]
	v_mfma_f32_16x16x32_bf16 v[18:21], v[146:149], v[214:217], v[18:21]
	v_mfma_f32_16x16x32_bf16 v[10:13], v[162:165], v[214:217], v[10:13]
	v_mfma_f32_16x16x32_bf16 v[62:65], v[158:161], v[190:193], v[62:65]
	v_mfma_f32_16x16x32_bf16 v[58:61], v[166:169], v[190:193], v[58:61]
	v_mfma_f32_16x16x32_bf16 v[50:53], v[158:161], v[198:201], v[50:53]
	v_mfma_f32_16x16x32_bf16 v[42:45], v[166:169], v[198:201], v[42:45]
	v_mfma_f32_16x16x32_bf16 v[34:37], v[158:161], v[206:209], v[34:37]
	v_mfma_f32_16x16x32_bf16 v[26:29], v[166:169], v[206:209], v[26:29]
	v_mfma_f32_16x16x32_bf16 v[18:21], v[158:161], v[218:221], v[18:21]
	v_mfma_f32_16x16x32_bf16 v[10:13], v[166:169], v[218:221], v[10:13]
	s_setprio 0
	s_setprio 1
	v_mfma_f32_16x16x32_bf16 v[54:57], v[170:173], v[186:189], v[54:57]
	v_mfma_f32_16x16x32_bf16 v[46:49], v[178:181], v[186:189], v[46:49]
	v_mfma_f32_16x16x32_bf16 v[38:41], v[170:173], v[194:197], v[38:41]
	v_mfma_f32_16x16x32_bf16 v[30:33], v[178:181], v[194:197], v[30:33]
	v_mfma_f32_16x16x32_bf16 v[22:25], v[170:173], v[202:205], v[22:25]
	v_mfma_f32_16x16x32_bf16 v[14:17], v[178:181], v[202:205], v[14:17]
	v_mfma_f32_16x16x32_bf16 v[6:9], v[170:173], v[214:217], v[6:9]
	v_mfma_f32_16x16x32_bf16 v[2:5], v[178:181], v[214:217], v[2:5]
	v_mfma_f32_16x16x32_bf16 v[54:57], v[174:177], v[190:193], v[54:57]
	v_mfma_f32_16x16x32_bf16 v[46:49], v[182:185], v[190:193], v[46:49]
	v_mfma_f32_16x16x32_bf16 v[38:41], v[174:177], v[198:201], v[38:41]
	v_mfma_f32_16x16x32_bf16 v[30:33], v[182:185], v[198:201], v[30:33]
	v_mfma_f32_16x16x32_bf16 v[22:25], v[174:177], v[206:209], v[22:25]
	v_mfma_f32_16x16x32_bf16 v[14:17], v[182:185], v[206:209], v[14:17]
	v_mfma_f32_16x16x32_bf16 v[6:9], v[174:177], v[218:221], v[6:9]
	v_mfma_f32_16x16x32_bf16 v[2:5], v[182:185], v[218:221], v[2:5]
	s_setprio 0
	s_add_i32 s59, s59, 2
	s_add_u32 s28, s28, 0x100
	s_addc_u32 s29, s29, 0
	s_add_u32 s57, s57, 0x100
	s_addc_u32 s58, s58, 0
	s_cmpk_gt_u32 s59, 0x7d
	s_barrier
	s_cbranch_scc0 .LBB0_1714
	s_and_b64 vcc, exec, s[8:9]
	s_cbranch_vccz .LBB0_1717
	s_barrier

.LBB0_1814:
	ds_read_b128 v[130:133], v171
	ds_read_b128 v[134:137], v171 offset:1024
	ds_read_b128 v[154:157], v171 offset:2048
	ds_read_b128 v[158:161], v171 offset:3072
	ds_read_b128 v[162:165], v172
	ds_read_b128 v[176:179], v172 offset:1024
	ds_read_b128 v[180:183], v172 offset:2048
	ds_read_b128 v[184:187], v172 offset:3072
	s_add_u32 s16, s8, 0xfff80080
	s_addc_u32 s17, s9, -1
	s_cmp_eq_u32 s52, 28
	s_cselect_b32 s35, s1, s17
	s_cselect_b32 s34, s7, s16
	s_cselect_b32 s17, s25, s51
	s_cselect_b32 s16, s27, s33
	v_lshl_add_u64 v[168:169], s[8:9], 0, v[146:147]
	s_add_i32 m0, s37, 0xc000
	ds_read_b128 v[188:191], v173
	ds_read_b128 v[192:195], v173 offset:1024
	ds_read_b128 v[196:199], v173 offset:2048
	ds_read_b128 v[200:203], v173 offset:3072
	ds_read_b128 v[204:207], v173 offset:4096
	ds_read_b128 v[208:211], v173 offset:5120
	ds_read_b128 v[214:217], v173 offset:6144
	ds_read_b128 v[218:221], v173 offset:7168
	global_load_lds_dwordx4 v[168:169], off
	v_lshl_add_u64 v[168:169], s[8:9], 0, v[148:149]
	s_add_i32 m0, s37, 0xe000
	s_nop 0
	global_load_lds_dwordx4 v[168:169], off
	s_waitcnt vmcnt(8)
	s_waitcnt lgkmcnt(0)
	s_barrier
	s_setprio 1
	s_waitcnt lgkmcnt(0)
	v_mfma_f32_16x16x32_bf16 v[126:129], v[130:133], v[188:191], v[126:129]
	v_mfma_f32_16x16x32_bf16 v[122:125], v[154:157], v[188:191], v[122:125]
	v_mfma_f32_16x16x32_bf16 v[110:113], v[130:133], v[196:199], v[110:113]
	v_mfma_f32_16x16x32_bf16 v[106:109], v[154:157], v[196:199], v[106:109]
	v_mfma_f32_16x16x32_bf16 v[94:97], v[130:133], v[204:207], v[94:97]
	v_mfma_f32_16x16x32_bf16 v[90:93], v[154:157], v[204:207], v[90:93]
	v_mfma_f32_16x16x32_bf16 v[78:81], v[130:133], v[214:217], v[78:81]
	v_mfma_f32_16x16x32_bf16 v[74:77], v[154:157], v[214:217], v[74:77]
	v_mfma_f32_16x16x32_bf16 v[126:129], v[134:137], v[192:195], v[126:129]
	v_mfma_f32_16x16x32_bf16 v[122:125], v[158:161], v[192:195], v[122:125]
	v_mfma_f32_16x16x32_bf16 v[110:113], v[134:137], v[200:203], v[110:113]
	v_mfma_f32_16x16x32_bf16 v[106:109], v[158:161], v[200:203], v[106:109]
	v_mfma_f32_16x16x32_bf16 v[94:97], v[134:137], v[208:211], v[94:97]
	v_mfma_f32_16x16x32_bf16 v[90:93], v[158:161], v[208:211], v[90:93]
	v_mfma_f32_16x16x32_bf16 v[78:81], v[134:137], v[218:221], v[78:81]
	v_mfma_f32_16x16x32_bf16 v[74:77], v[158:161], v[218:221], v[74:77]
	s_setprio 0
	s_setprio 1
	v_mfma_f32_16x16x32_bf16 v[118:121], v[162:165], v[188:191], v[118:121]
	v_mfma_f32_16x16x32_bf16 v[114:117], v[180:183], v[188:191], v[114:117]
	v_mfma_f32_16x16x32_bf16 v[102:105], v[162:165], v[196:199], v[102:105]
	v_mfma_f32_16x16x32_bf16 v[98:101], v[180:183], v[196:199], v[98:101]
	v_mfma_f32_16x16x32_bf16 v[86:89], v[162:165], v[204:207], v[86:89]
	v_mfma_f32_16x16x32_bf16 v[82:85], v[180:183], v[204:207], v[82:85]
	v_mfma_f32_16x16x32_bf16 v[70:73], v[162:165], v[214:217], v[70:73]
	v_mfma_f32_16x16x32_bf16 v[66:69], v[180:183], v[214:217], v[66:69]
	v_mfma_f32_16x16x32_bf16 v[118:121], v[176:179], v[192:195], v[118:121]
	v_mfma_f32_16x16x32_bf16 v[114:117], v[184:187], v[192:195], v[114:117]
	v_mfma_f32_16x16x32_bf16 v[102:105], v[176:179], v[200:203], v[102:105]
	v_mfma_f32_16x16x32_bf16 v[98:101], v[184:187], v[200:203], v[98:101]
	v_mfma_f32_16x16x32_bf16 v[86:89], v[176:179], v[208:211], v[86:89]
	v_mfma_f32_16x16x32_bf16 v[82:85], v[184:187], v[208:211], v[82:85]
	v_mfma_f32_16x16x32_bf16 v[70:73], v[176:179], v[218:221], v[70:73]
	v_mfma_f32_16x16x32_bf16 v[66:69], v[184:187], v[218:221], v[66:69]
	s_setprio 0
	s_barrier
	s_add_i32 s53, s48, s36
	v_lshl_add_u64 v[168:169], s[16:17], 0, v[140:141]
	s_mov_b32 m0, s53
	ds_read_b128 v[188:191], v173 offset:16384
	ds_read_b128 v[192:195], v173 offset:17408
	ds_read_b128 v[196:199], v173 offset:18432
	ds_read_b128 v[200:203], v173 offset:19456
	ds_read_b128 v[204:207], v173 offset:20480
	ds_read_b128 v[208:211], v173 offset:21504
	ds_read_b128 v[214:217], v173 offset:22528
	ds_read_b128 v[218:221], v173 offset:23552
	global_load_lds_dwordx4 v[168:169], off
	s_add_i32 m0, s53, 0x2000
	s_add_u32 s54, s16, 0x80000
	v_lshl_add_u64 v[222:223], s[16:17], 0, v[144:145]
	s_addc_u32 s55, s17, 0
	s_add_i32 s53, s49, s36
	global_load_lds_dwordx4 v[222:223], off
	v_lshl_add_u64 v[224:225], s[54:55], 0, v[140:141]
	s_mov_b32 m0, s53
	v_lshl_add_u64 v[226:227], s[34:35], 0, v[142:143]
	global_load_lds_dwordx4 v[224:225], off
	v_lshl_add_u64 v[224:225], s[54:55], 0, v[144:145]
	s_add_i32 m0, s53, 0x2000
	s_nop 0
	global_load_lds_dwordx4 v[224:225], off
	v_lshl_add_u64 v[224:225], s[34:35], 0, v[138:139]
	s_mov_b32 m0, s37
	s_nop 0
	global_load_lds_dwordx4 v[224:225], off
	s_mov_b32 m0, s38
	s_nop 0
	global_load_lds_dwordx4 v[226:227], off
	s_waitcnt vmcnt(8)
	s_waitcnt lgkmcnt(0)
	s_barrier
	s_setprio 1
	s_waitcnt lgkmcnt(0)
	v_mfma_f32_16x16x32_bf16 v[62:65], v[130:133], v[188:191], v[62:65]
	v_mfma_f32_16x16x32_bf16 v[58:61], v[154:157], v[188:191], v[58:61]
	v_mfma_f32_16x16x32_bf16 v[46:49], v[130:133], v[196:199], v[46:49]
	v_mfma_f32_16x16x32_bf16 v[42:45], v[154:157], v[196:199], v[42:45]
	v_mfma_f32_16x16x32_bf16 v[30:33], v[130:133], v[204:207], v[30:33]
	v_mfma_f32_16x16x32_bf16 v[26:29], v[154:157], v[204:207], v[26:29]
	v_mfma_f32_16x16x32_bf16 v[14:17], v[130:133], v[214:217], v[14:17]
	v_mfma_f32_16x16x32_bf16 v[10:13], v[154:157], v[214:217], v[10:13]
	v_mfma_f32_16x16x32_bf16 v[62:65], v[134:137], v[192:195], v[62:65]
	v_mfma_f32_16x16x32_bf16 v[58:61], v[158:161], v[192:195], v[58:61]
	v_mfma_f32_16x16x32_bf16 v[46:49], v[134:137], v[200:203], v[46:49]
	v_mfma_f32_16x16x32_bf16 v[42:45], v[158:161], v[200:203], v[42:45]
	v_mfma_f32_16x16x32_bf16 v[30:33], v[134:137], v[208:211], v[30:33]
	v_mfma_f32_16x16x32_bf16 v[26:29], v[158:161], v[208:211], v[26:29]
	v_mfma_f32_16x16x32_bf16 v[14:17], v[134:137], v[218:221], v[14:17]
	v_mfma_f32_16x16x32_bf16 v[10:13], v[158:161], v[218:221], v[10:13]
	s_setprio 0
	s_setprio 1
	v_mfma_f32_16x16x32_bf16 v[54:57], v[162:165], v[188:191], v[54:57]
	v_mfma_f32_16x16x32_bf16 v[50:53], v[180:183], v[188:191], v[50:53]
	v_mfma_f32_16x16x32_bf16 v[38:41], v[162:165], v[196:199], v[38:41]
	v_mfma_f32_16x16x32_bf16 v[34:37], v[180:183], v[196:199], v[34:37]
	v_mfma_f32_16x16x32_bf16 v[22:25], v[162:165], v[204:207], v[22:25]
	v_mfma_f32_16x16x32_bf16 v[18:21], v[180:183], v[204:207], v[18:21]
	v_mfma_f32_16x16x32_bf16 v[6:9], v[162:165], v[214:217], v[6:9]
	v_mfma_f32_16x16x32_bf16 v[2:5], v[180:183], v[214:217], v[2:5]
	v_mfma_f32_16x16x32_bf16 v[54:57], v[176:179], v[192:195], v[54:57]
	v_mfma_f32_16x16x32_bf16 v[50:53], v[184:187], v[192:195], v[50:53]
	v_mfma_f32_16x16x32_bf16 v[38:41], v[176:179], v[200:203], v[38:41]
	v_mfma_f32_16x16x32_bf16 v[34:37], v[184:187], v[200:203], v[34:37]
	v_mfma_f32_16x16x32_bf16 v[22:25], v[176:179], v[208:211], v[22:25]
	v_mfma_f32_16x16x32_bf16 v[18:21], v[184:187], v[208:211], v[18:21]
	v_mfma_f32_16x16x32_bf16 v[6:9], v[176:179], v[218:221], v[6:9]
	v_mfma_f32_16x16x32_bf16 v[2:5], v[184:187], v[218:221], v[2:5]
	s_setprio 0
	s_barrier
	s_add_i32 s53, 0, 0x18000
	s_add_i32 s54, 0, 0x1c000
	v_add_u32_e32 v158, s53, v167
	v_add_u32_e32 v166, s54, v167
	ds_read_b128 v[130:133], v158
	ds_read_b128 v[134:137], v158 offset:1024
	ds_read_b128 v[154:157], v158 offset:2048
	ds_read_b128 v[158:161], v158 offset:3072
	ds_read_b128 v[162:165], v166
	ds_read_b128 v[176:179], v166 offset:1024
	ds_read_b128 v[180:183], v166 offset:2048
	ds_read_b128 v[184:187], v166 offset:3072
	s_add_u32 s34, s34, 0x80000
	s_addc_u32 s35, s35, 0
	s_mov_b32 m0, s39
	v_lshl_add_u64 v[228:229], s[34:35], 0, v[138:139]
	ds_read_b128 v[188:191], v173 offset:32768
	ds_read_b128 v[192:195], v173 offset:33792
	ds_read_b128 v[196:199], v173 offset:34816
	ds_read_b128 v[200:203], v173 offset:35840
	ds_read_b128 v[204:207], v173 offset:36864
	ds_read_b128 v[208:211], v173 offset:37888
	ds_read_b128 v[214:217], v173 offset:38912
	ds_read_b128 v[218:221], v173 offset:39936
	global_load_lds_dwordx4 v[228:229], off
	v_lshl_add_u64 v[228:229], s[34:35], 0, v[142:143]
	s_mov_b32 m0, s40
	s_nop 0
	global_load_lds_dwordx4 v[228:229], off
	s_waitcnt vmcnt(8)
	s_waitcnt lgkmcnt(0)
	s_barrier
	s_setprio 1
	s_waitcnt lgkmcnt(0)
	v_mfma_f32_16x16x32_bf16 v[126:129], v[130:133], v[188:191], v[126:129]
	v_mfma_f32_16x16x32_bf16 v[122:125], v[154:157], v[188:191], v[122:125]
	v_mfma_f32_16x16x32_bf16 v[110:113], v[130:133], v[196:199], v[110:113]
	v_mfma_f32_16x16x32_bf16 v[106:109], v[154:157], v[196:199], v[106:109]
	v_mfma_f32_16x16x32_bf16 v[94:97], v[130:133], v[204:207], v[94:97]
	v_mfma_f32_16x16x32_bf16 v[90:93], v[154:157], v[204:207], v[90:93]
	v_mfma_f32_16x16x32_bf16 v[78:81], v[130:133], v[214:217], v[78:81]
	v_mfma_f32_16x16x32_bf16 v[74:77], v[154:157], v[214:217], v[74:77]
	v_mfma_f32_16x16x32_bf16 v[126:129], v[134:137], v[192:195], v[126:129]
	v_mfma_f32_16x16x32_bf16 v[122:125], v[158:161], v[192:195], v[122:125]
	v_mfma_f32_16x16x32_bf16 v[110:113], v[134:137], v[200:203], v[110:113]
	v_mfma_f32_16x16x32_bf16 v[106:109], v[158:161], v[200:203], v[106:109]
	v_mfma_f32_16x16x32_bf16 v[94:97], v[134:137], v[208:211], v[94:97]
	v_mfma_f32_16x16x32_bf16 v[90:93], v[158:161], v[208:211], v[90:93]
	v_mfma_f32_16x16x32_bf16 v[78:81], v[134:137], v[218:221], v[78:81]
	v_mfma_f32_16x16x32_bf16 v[74:77], v[158:161], v[218:221], v[74:77]
	s_setprio 0
	s_setprio 1
	v_mfma_f32_16x16x32_bf16 v[118:121], v[162:165], v[188:191], v[118:121]
	v_mfma_f32_16x16x32_bf16 v[114:117], v[180:183], v[188:191], v[114:117]
	v_mfma_f32_16x16x32_bf16 v[102:105], v[162:165], v[196:199], v[102:105]
	v_mfma_f32_16x16x32_bf16 v[98:101], v[180:183], v[196:199], v[98:101]
	v_mfma_f32_16x16x32_bf16 v[86:89], v[162:165], v[204:207], v[86:89]
	v_mfma_f32_16x16x32_bf16 v[82:85], v[180:183], v[204:207], v[82:85]
	v_mfma_f32_16x16x32_bf16 v[70:73], v[162:165], v[214:217], v[70:73]
	v_mfma_f32_16x16x32_bf16 v[66:69], v[180:183], v[214:217], v[66:69]
	v_mfma_f32_16x16x32_bf16 v[118:121], v[176:179], v[192:195], v[118:121]
	v_mfma_f32_16x16x32_bf16 v[114:117], v[184:187], v[192:195], v[114:117]
	v_mfma_f32_16x16x32_bf16 v[102:105], v[176:179], v[200:203], v[102:105]
	v_mfma_f32_16x16x32_bf16 v[98:101], v[184:187], v[200:203], v[98:101]
	v_mfma_f32_16x16x32_bf16 v[86:89], v[176:179], v[208:211], v[86:89]
	v_mfma_f32_16x16x32_bf16 v[82:85], v[184:187], v[208:211], v[82:85]
	v_mfma_f32_16x16x32_bf16 v[70:73], v[176:179], v[218:221], v[70:73]
	v_mfma_f32_16x16x32_bf16 v[66:69], v[184:187], v[218:221], v[66:69]
	s_setprio 0
	s_barrier
	s_add_i32 s34, s53, s36
	v_lshl_add_u64 v[168:169], v[168:169], 0, s[20:21]
	s_mov_b32 m0, s34
	ds_read_b128 v[188:191], v173 offset:49152
	ds_read_b128 v[192:195], v173 offset:50176
	ds_read_b128 v[196:199], v173 offset:51200
	ds_read_b128 v[200:203], v173 offset:52224
	ds_read_b128 v[204:207], v173 offset:53248
	ds_read_b128 v[208:211], v173 offset:54272
	ds_read_b128 v[214:217], v173 offset:55296
	ds_read_b128 v[218:221], v173 offset:56320
	global_load_lds_dwordx4 v[168:169], off
	s_add_i32 m0, s34, 0x2000
	s_add_u32 s16, s16, 0x80080
	v_lshl_add_u64 v[168:169], v[222:223], 0, s[20:21]
	s_addc_u32 s17, s17, 0
	s_add_i32 s34, s54, s36
	global_load_lds_dwordx4 v[168:169], off
	v_lshl_add_u64 v[168:169], s[16:17], 0, v[140:141]
	s_mov_b32 m0, s34
	s_nop 0
	global_load_lds_dwordx4 v[168:169], off
	v_lshl_add_u64 v[168:169], s[16:17], 0, v[144:145]
	s_add_i32 m0, s34, 0x2000
	s_nop 0
	global_load_lds_dwordx4 v[168:169], off
	v_lshl_add_u64 v[168:169], v[224:225], 0, s[20:21]
	s_mov_b32 m0, s42
	s_nop 0
	global_load_lds_dwordx4 v[168:169], off
	v_lshl_add_u64 v[168:169], v[226:227], 0, s[20:21]
	s_mov_b32 m0, s43
	s_nop 0
	global_load_lds_dwordx4 v[168:169], off
	s_waitcnt vmcnt(8)
	s_waitcnt lgkmcnt(0)
	s_barrier
	s_setprio 1
	s_waitcnt lgkmcnt(0)
	v_mfma_f32_16x16x32_bf16 v[62:65], v[130:133], v[188:191], v[62:65]
	v_mfma_f32_16x16x32_bf16 v[58:61], v[154:157], v[188:191], v[58:61]
	v_mfma_f32_16x16x32_bf16 v[46:49], v[130:133], v[196:199], v[46:49]
	v_mfma_f32_16x16x32_bf16 v[42:45], v[154:157], v[196:199], v[42:45]
	v_mfma_f32_16x16x32_bf16 v[30:33], v[130:133], v[204:207], v[30:33]
	v_mfma_f32_16x16x32_bf16 v[26:29], v[154:157], v[204:207], v[26:29]
	v_mfma_f32_16x16x32_bf16 v[14:17], v[130:133], v[214:217], v[14:17]
	v_mfma_f32_16x16x32_bf16 v[10:13], v[154:157], v[214:217], v[10:13]
	v_mfma_f32_16x16x32_bf16 v[62:65], v[134:137], v[192:195], v[62:65]
	v_mfma_f32_16x16x32_bf16 v[58:61], v[158:161], v[192:195], v[58:61]
	v_mfma_f32_16x16x32_bf16 v[46:49], v[134:137], v[200:203], v[46:49]
	v_mfma_f32_16x16x32_bf16 v[42:45], v[158:161], v[200:203], v[42:45]
	v_mfma_f32_16x16x32_bf16 v[30:33], v[134:137], v[208:211], v[30:33]
	v_mfma_f32_16x16x32_bf16 v[26:29], v[158:161], v[208:211], v[26:29]
	v_mfma_f32_16x16x32_bf16 v[14:17], v[134:137], v[218:221], v[14:17]
	v_mfma_f32_16x16x32_bf16 v[10:13], v[158:161], v[218:221], v[10:13]
	s_setprio 0
	s_setprio 1
	v_mfma_f32_16x16x32_bf16 v[54:57], v[162:165], v[188:191], v[54:57]
	v_mfma_f32_16x16x32_bf16 v[50:53], v[180:183], v[188:191], v[50:53]
	v_mfma_f32_16x16x32_bf16 v[38:41], v[162:165], v[196:199], v[38:41]
	v_mfma_f32_16x16x32_bf16 v[34:37], v[180:183], v[196:199], v[34:37]
	v_mfma_f32_16x16x32_bf16 v[22:25], v[162:165], v[204:207], v[22:25]
	v_mfma_f32_16x16x32_bf16 v[18:21], v[180:183], v[204:207], v[18:21]
	v_mfma_f32_16x16x32_bf16 v[6:9], v[162:165], v[214:217], v[6:9]
	v_mfma_f32_16x16x32_bf16 v[2:5], v[180:183], v[214:217], v[2:5]
	v_mfma_f32_16x16x32_bf16 v[54:57], v[176:179], v[192:195], v[54:57]
	v_mfma_f32_16x16x32_bf16 v[50:53], v[184:187], v[192:195], v[50:53]
	v_mfma_f32_16x16x32_bf16 v[38:41], v[176:179], v[200:203], v[38:41]
	v_mfma_f32_16x16x32_bf16 v[34:37], v[184:187], v[200:203], v[34:37]
	v_mfma_f32_16x16x32_bf16 v[22:25], v[176:179], v[208:211], v[22:25]
	v_mfma_f32_16x16x32_bf16 v[18:21], v[184:187], v[208:211], v[18:21]
	v_mfma_f32_16x16x32_bf16 v[6:9], v[176:179], v[218:221], v[6:9]
	v_mfma_f32_16x16x32_bf16 v[2:5], v[184:187], v[218:221], v[2:5]
	s_setprio 0
	s_add_i32 s52, s52, 2
	s_add_u32 s8, s8, 0x100
	s_addc_u32 s9, s9, 0
	s_add_u32 s33, s33, 0x100
	s_addc_u32 s51, s51, 0
	s_cmp_gt_u32 s52, 29
	s_barrier
	s_cbranch_scc0 .LBB0_1814
	s_and_b64 vcc, exec, s[22:23]
	s_cbranch_vccz .LBB0_1817
	s_barrier

.LBB0_1911:
	v_add_u32_e32 v153, s43, v151
	ds_read_b128 v[154:157], v153
	ds_read_b128 v[158:161], v153 offset:1024
	ds_read_b128 v[162:165], v153 offset:2048
	ds_read_b128 v[166:169], v153 offset:3072
	v_add_u32_e32 v153, s44, v151
	s_add_u32 s26, s8, s24
	ds_read_b128 v[172:175], v153
	ds_read_b128 v[176:179], v153 offset:1024
	ds_read_b128 v[180:183], v153 offset:2048
	ds_read_b128 v[184:187], v153 offset:3072
	s_addc_u32 s27, s9, s25
	s_add_u32 s26, s26, 0x100
	s_addc_u32 s27, s27, 0
	s_add_u32 s51, s21, s24
	s_addc_u32 s52, s45, s25
	s_cmpk_eq_i32 s24, 0xf00
	s_cselect_b32 s29, s17, s27
	s_cselect_b32 s28, s48, s26
	s_cselect_b32 s27, s15, s52
	s_cselect_b32 s26, s49, s51
	v_lshl_add_u64 v[222:223], v[146:147], 0, s[24:25]
	s_add_i32 m0, s35, 0xc000
	ds_read_b128 v[188:191], v152
	ds_read_b128 v[192:195], v152 offset:1024
	ds_read_b128 v[196:199], v152 offset:2048
	ds_read_b128 v[200:203], v152 offset:3072
	ds_read_b128 v[204:207], v152 offset:4096
	ds_read_b128 v[208:211], v152 offset:5120
	ds_read_b128 v[214:217], v152 offset:6144
	ds_read_b128 v[218:221], v152 offset:7168
	global_load_lds_dwordx4 v[222:223], off
	v_lshl_add_u64 v[222:223], v[148:149], 0, s[24:25]
	s_add_i32 m0, s35, 0xe000
	s_nop 0
	global_load_lds_dwordx4 v[222:223], off
	s_waitcnt vmcnt(8)
	s_waitcnt lgkmcnt(0)
	s_barrier
	s_setprio 1
	s_waitcnt lgkmcnt(0)
	v_mfma_f32_16x16x32_bf16 v[38:41], v[154:157], v[188:191], v[38:41]
	v_mfma_f32_16x16x32_bf16 v[138:141], v[162:165], v[188:191], v[138:141]
	v_mfma_f32_16x16x32_bf16 v[70:73], v[154:157], v[196:199], v[70:73]
	v_mfma_f32_16x16x32_bf16 v[134:137], v[162:165], v[196:199], v[134:137]
	v_mfma_f32_16x16x32_bf16 v[98:101], v[154:157], v[204:207], v[98:101]
	v_mfma_f32_16x16x32_bf16 v[130:133], v[162:165], v[204:207], v[130:133]
	v_mfma_f32_16x16x32_bf16 v[126:129], v[154:157], v[214:217], v[126:129]
	v_mfma_f32_16x16x32_bf16 v[122:125], v[162:165], v[214:217], v[122:125]
	v_mfma_f32_16x16x32_bf16 v[38:41], v[158:161], v[192:195], v[38:41]
	v_mfma_f32_16x16x32_bf16 v[138:141], v[166:169], v[192:195], v[138:141]
	v_mfma_f32_16x16x32_bf16 v[70:73], v[158:161], v[200:203], v[70:73]
	v_mfma_f32_16x16x32_bf16 v[134:137], v[166:169], v[200:203], v[134:137]
	v_mfma_f32_16x16x32_bf16 v[98:101], v[158:161], v[208:211], v[98:101]
	v_mfma_f32_16x16x32_bf16 v[130:133], v[166:169], v[208:211], v[130:133]
	v_mfma_f32_16x16x32_bf16 v[126:129], v[158:161], v[218:221], v[126:129]
	v_mfma_f32_16x16x32_bf16 v[122:125], v[166:169], v[218:221], v[122:125]
	s_setprio 0
	s_setprio 1
	v_mfma_f32_16x16x32_bf16 v[48:51], v[172:175], v[188:191], v[48:51]
	v_mfma_f32_16x16x32_bf16 v[58:61], v[180:183], v[188:191], v[58:61]
	v_mfma_f32_16x16x32_bf16 v[80:83], v[172:175], v[196:199], v[80:83]
	v_mfma_f32_16x16x32_bf16 v[90:93], v[180:183], v[196:199], v[90:93]
	v_mfma_f32_16x16x32_bf16 v[108:111], v[172:175], v[204:207], v[108:111]
	v_mfma_f32_16x16x32_bf16 v[118:121], v[180:183], v[204:207], v[118:121]
	v_mfma_f32_16x16x32_bf16 v[114:117], v[172:175], v[214:217], v[114:117]
	v_mfma_f32_16x16x32_bf16 v[102:105], v[180:183], v[214:217], v[102:105]
	v_mfma_f32_16x16x32_bf16 v[48:51], v[176:179], v[192:195], v[48:51]
	v_mfma_f32_16x16x32_bf16 v[58:61], v[184:187], v[192:195], v[58:61]
	v_mfma_f32_16x16x32_bf16 v[80:83], v[176:179], v[200:203], v[80:83]
	v_mfma_f32_16x16x32_bf16 v[90:93], v[184:187], v[200:203], v[90:93]
	v_mfma_f32_16x16x32_bf16 v[108:111], v[176:179], v[208:211], v[108:111]
	v_mfma_f32_16x16x32_bf16 v[118:121], v[184:187], v[208:211], v[118:121]
	v_mfma_f32_16x16x32_bf16 v[114:117], v[176:179], v[218:221], v[114:117]
	v_mfma_f32_16x16x32_bf16 v[102:105], v[184:187], v[218:221], v[102:105]
	s_setprio 0
	s_barrier
	s_add_i32 s51, s43, s34
	v_lshl_add_u64 v[222:223], s[26:27], 0, v[52:53]
	s_mov_b32 m0, s51
	ds_read_b128 v[188:191], v152 offset:16384
	ds_read_b128 v[192:195], v152 offset:17408
	ds_read_b128 v[196:199], v152 offset:18432
	ds_read_b128 v[200:203], v152 offset:19456
	ds_read_b128 v[204:207], v152 offset:20480
	ds_read_b128 v[208:211], v152 offset:21504
	ds_read_b128 v[214:217], v152 offset:22528
	ds_read_b128 v[218:221], v152 offset:23552
	global_load_lds_dwordx4 v[222:223], off
	s_add_i32 m0, s51, 0x2000
	s_add_u32 s52, s26, 0x80000
	v_lshl_add_u64 v[224:225], s[26:27], 0, v[84:85]
	s_addc_u32 s53, s27, 0
	s_add_i32 s51, s44, s34
	global_load_lds_dwordx4 v[224:225], off
	v_lshl_add_u64 v[226:227], s[52:53], 0, v[52:53]
	s_mov_b32 m0, s51
	v_lshl_add_u64 v[228:229], s[28:29], 0, v[78:79]
	global_load_lds_dwordx4 v[226:227], off
	v_lshl_add_u64 v[226:227], s[52:53], 0, v[84:85]
	s_add_i32 m0, s51, 0x2000
	s_nop 0
	global_load_lds_dwordx4 v[226:227], off
	v_lshl_add_u64 v[226:227], s[28:29], 0, v[46:47]
	s_mov_b32 m0, s35
	s_nop 0
	global_load_lds_dwordx4 v[226:227], off
	s_mov_b32 m0, s36
	s_nop 0
	global_load_lds_dwordx4 v[228:229], off
	s_waitcnt vmcnt(8)
	s_waitcnt lgkmcnt(0)
	s_barrier
	s_setprio 1
	s_waitcnt lgkmcnt(0)
	v_mfma_f32_16x16x32_bf16 v[94:97], v[154:157], v[188:191], v[94:97]
	v_mfma_f32_16x16x32_bf16 v[86:89], v[162:165], v[188:191], v[86:89]
	v_mfma_f32_16x16x32_bf16 v[62:65], v[154:157], v[196:199], v[62:65]
	v_mfma_f32_16x16x32_bf16 v[54:57], v[162:165], v[196:199], v[54:57]
	v_mfma_f32_16x16x32_bf16 v[30:33], v[154:157], v[204:207], v[30:33]
	v_mfma_f32_16x16x32_bf16 v[26:29], v[162:165], v[204:207], v[26:29]
	v_mfma_f32_16x16x32_bf16 v[14:17], v[154:157], v[214:217], v[14:17]
	v_mfma_f32_16x16x32_bf16 v[10:13], v[162:165], v[214:217], v[10:13]
	v_mfma_f32_16x16x32_bf16 v[94:97], v[158:161], v[192:195], v[94:97]
	v_mfma_f32_16x16x32_bf16 v[86:89], v[166:169], v[192:195], v[86:89]
	v_mfma_f32_16x16x32_bf16 v[62:65], v[158:161], v[200:203], v[62:65]
	v_mfma_f32_16x16x32_bf16 v[54:57], v[166:169], v[200:203], v[54:57]
	v_mfma_f32_16x16x32_bf16 v[30:33], v[158:161], v[208:211], v[30:33]
	v_mfma_f32_16x16x32_bf16 v[26:29], v[166:169], v[208:211], v[26:29]
	v_mfma_f32_16x16x32_bf16 v[14:17], v[158:161], v[218:221], v[14:17]
	v_mfma_f32_16x16x32_bf16 v[10:13], v[166:169], v[218:221], v[10:13]
	s_setprio 0
	s_setprio 1
	v_mfma_f32_16x16x32_bf16 v[74:77], v[172:175], v[188:191], v[74:77]
	v_mfma_f32_16x16x32_bf16 v[66:69], v[180:183], v[188:191], v[66:69]
	v_mfma_f32_16x16x32_bf16 v[42:45], v[172:175], v[196:199], v[42:45]
	v_mfma_f32_16x16x32_bf16 v[34:37], v[180:183], v[196:199], v[34:37]
	v_mfma_f32_16x16x32_bf16 v[22:25], v[172:175], v[204:207], v[22:25]
	v_mfma_f32_16x16x32_bf16 v[18:21], v[180:183], v[204:207], v[18:21]
	v_mfma_f32_16x16x32_bf16 v[6:9], v[172:175], v[214:217], v[6:9]
	v_mfma_f32_16x16x32_bf16 v[2:5], v[180:183], v[214:217], v[2:5]
	v_mfma_f32_16x16x32_bf16 v[74:77], v[176:179], v[192:195], v[74:77]
	v_mfma_f32_16x16x32_bf16 v[66:69], v[184:187], v[192:195], v[66:69]
	v_mfma_f32_16x16x32_bf16 v[42:45], v[176:179], v[200:203], v[42:45]
	v_mfma_f32_16x16x32_bf16 v[34:37], v[184:187], v[200:203], v[34:37]
	v_mfma_f32_16x16x32_bf16 v[22:25], v[176:179], v[208:211], v[22:25]
	v_mfma_f32_16x16x32_bf16 v[18:21], v[184:187], v[208:211], v[18:21]
	v_mfma_f32_16x16x32_bf16 v[6:9], v[176:179], v[218:221], v[6:9]
	v_mfma_f32_16x16x32_bf16 v[2:5], v[184:187], v[218:221], v[2:5]
	s_setprio 0
	s_barrier
	s_add_i32 s51, 0, 0x18000
	v_add_u32_e32 v153, s51, v151
	s_add_i32 s52, 0, 0x1c000
	ds_read_b128 v[154:157], v153
	ds_read_b128 v[158:161], v153 offset:1024
	ds_read_b128 v[162:165], v153 offset:2048
	ds_read_b128 v[166:169], v153 offset:3072
	v_add_u32_e32 v153, s52, v151
	ds_read_b128 v[172:175], v153
	ds_read_b128 v[176:179], v153 offset:1024
	ds_read_b128 v[180:183], v153 offset:2048
	ds_read_b128 v[184:187], v153 offset:3072
	s_add_u32 s28, s28, 0x80000
	s_addc_u32 s29, s29, 0
	s_mov_b32 m0, s37
	v_lshl_add_u64 v[230:231], s[28:29], 0, v[46:47]
	ds_read_b128 v[188:191], v152 offset:32768
	ds_read_b128 v[192:195], v152 offset:33792
	ds_read_b128 v[196:199], v152 offset:34816
	ds_read_b128 v[200:203], v152 offset:35840
	ds_read_b128 v[204:207], v152 offset:36864
	ds_read_b128 v[208:211], v152 offset:37888
	ds_read_b128 v[214:217], v152 offset:38912
	ds_read_b128 v[218:221], v152 offset:39936
	global_load_lds_dwordx4 v[230:231], off
	v_lshl_add_u64 v[230:231], s[28:29], 0, v[78:79]
	s_mov_b32 m0, s38
	s_nop 0
	global_load_lds_dwordx4 v[230:231], off
	s_waitcnt vmcnt(8)
	s_waitcnt lgkmcnt(0)
	s_barrier
	s_setprio 1
	s_waitcnt lgkmcnt(0)
	v_mfma_f32_16x16x32_bf16 v[38:41], v[154:157], v[188:191], v[38:41]
	v_mfma_f32_16x16x32_bf16 v[138:141], v[162:165], v[188:191], v[138:141]
	v_mfma_f32_16x16x32_bf16 v[70:73], v[154:157], v[196:199], v[70:73]
	v_mfma_f32_16x16x32_bf16 v[134:137], v[162:165], v[196:199], v[134:137]
	v_mfma_f32_16x16x32_bf16 v[98:101], v[154:157], v[204:207], v[98:101]
	v_mfma_f32_16x16x32_bf16 v[130:133], v[162:165], v[204:207], v[130:133]
	v_mfma_f32_16x16x32_bf16 v[126:129], v[154:157], v[214:217], v[126:129]
	v_mfma_f32_16x16x32_bf16 v[122:125], v[162:165], v[214:217], v[122:125]
	v_mfma_f32_16x16x32_bf16 v[38:41], v[158:161], v[192:195], v[38:41]
	v_mfma_f32_16x16x32_bf16 v[138:141], v[166:169], v[192:195], v[138:141]
	v_mfma_f32_16x16x32_bf16 v[70:73], v[158:161], v[200:203], v[70:73]
	v_mfma_f32_16x16x32_bf16 v[134:137], v[166:169], v[200:203], v[134:137]
	v_mfma_f32_16x16x32_bf16 v[98:101], v[158:161], v[208:211], v[98:101]
	v_mfma_f32_16x16x32_bf16 v[130:133], v[166:169], v[208:211], v[130:133]
	v_mfma_f32_16x16x32_bf16 v[126:129], v[158:161], v[218:221], v[126:129]
	v_mfma_f32_16x16x32_bf16 v[122:125], v[166:169], v[218:221], v[122:125]
	s_setprio 0
	s_setprio 1
	v_mfma_f32_16x16x32_bf16 v[48:51], v[172:175], v[188:191], v[48:51]
	v_mfma_f32_16x16x32_bf16 v[58:61], v[180:183], v[188:191], v[58:61]
	v_mfma_f32_16x16x32_bf16 v[80:83], v[172:175], v[196:199], v[80:83]
	v_mfma_f32_16x16x32_bf16 v[90:93], v[180:183], v[196:199], v[90:93]
	v_mfma_f32_16x16x32_bf16 v[108:111], v[172:175], v[204:207], v[108:111]
	v_mfma_f32_16x16x32_bf16 v[118:121], v[180:183], v[204:207], v[118:121]
	v_mfma_f32_16x16x32_bf16 v[114:117], v[172:175], v[214:217], v[114:117]
	v_mfma_f32_16x16x32_bf16 v[102:105], v[180:183], v[214:217], v[102:105]
	v_mfma_f32_16x16x32_bf16 v[48:51], v[176:179], v[192:195], v[48:51]
	v_mfma_f32_16x16x32_bf16 v[58:61], v[184:187], v[192:195], v[58:61]
	v_mfma_f32_16x16x32_bf16 v[80:83], v[176:179], v[200:203], v[80:83]
	v_mfma_f32_16x16x32_bf16 v[90:93], v[184:187], v[200:203], v[90:93]
	v_mfma_f32_16x16x32_bf16 v[108:111], v[176:179], v[208:211], v[108:111]
	v_mfma_f32_16x16x32_bf16 v[118:121], v[184:187], v[208:211], v[118:121]
	v_mfma_f32_16x16x32_bf16 v[114:117], v[176:179], v[218:221], v[114:117]
	v_mfma_f32_16x16x32_bf16 v[102:105], v[184:187], v[218:221], v[102:105]
	s_setprio 0
	s_barrier
	s_add_i32 s28, s51, s34
	v_lshl_add_u64 v[222:223], v[222:223], 0, s[12:13]
	s_mov_b32 m0, s28
	ds_read_b128 v[188:191], v152 offset:49152
	ds_read_b128 v[192:195], v152 offset:50176
	ds_read_b128 v[196:199], v152 offset:51200
	ds_read_b128 v[200:203], v152 offset:52224
	ds_read_b128 v[204:207], v152 offset:53248
	ds_read_b128 v[208:211], v152 offset:54272
	ds_read_b128 v[214:217], v152 offset:55296
	ds_read_b128 v[218:221], v152 offset:56320
	global_load_lds_dwordx4 v[222:223], off
	s_add_i32 m0, s28, 0x2000
	s_add_u32 s26, s26, 0x80080
	v_lshl_add_u64 v[222:223], v[224:225], 0, s[12:13]
	s_addc_u32 s27, s27, 0
	s_add_i32 s28, s52, s34
	global_load_lds_dwordx4 v[222:223], off
	v_lshl_add_u64 v[222:223], s[26:27], 0, v[52:53]
	s_mov_b32 m0, s28
	s_nop 0
	global_load_lds_dwordx4 v[222:223], off
	v_lshl_add_u64 v[222:223], s[26:27], 0, v[84:85]
	s_add_i32 m0, s28, 0x2000
	s_nop 0
	global_load_lds_dwordx4 v[222:223], off
	v_lshl_add_u64 v[222:223], v[226:227], 0, s[12:13]
	s_mov_b32 m0, s41
	s_nop 0
	global_load_lds_dwordx4 v[222:223], off
	v_lshl_add_u64 v[222:223], v[228:229], 0, s[12:13]
	s_mov_b32 m0, s42
	s_nop 0
	global_load_lds_dwordx4 v[222:223], off
	s_waitcnt vmcnt(8)
	s_waitcnt lgkmcnt(0)
	s_barrier
	s_setprio 1
	s_waitcnt lgkmcnt(0)
	v_mfma_f32_16x16x32_bf16 v[94:97], v[154:157], v[188:191], v[94:97]
	v_mfma_f32_16x16x32_bf16 v[86:89], v[162:165], v[188:191], v[86:89]
	v_mfma_f32_16x16x32_bf16 v[62:65], v[154:157], v[196:199], v[62:65]
	v_mfma_f32_16x16x32_bf16 v[54:57], v[162:165], v[196:199], v[54:57]
	v_mfma_f32_16x16x32_bf16 v[30:33], v[154:157], v[204:207], v[30:33]
	v_mfma_f32_16x16x32_bf16 v[26:29], v[162:165], v[204:207], v[26:29]
	v_mfma_f32_16x16x32_bf16 v[14:17], v[154:157], v[214:217], v[14:17]
	v_mfma_f32_16x16x32_bf16 v[10:13], v[162:165], v[214:217], v[10:13]
	v_mfma_f32_16x16x32_bf16 v[94:97], v[158:161], v[192:195], v[94:97]
	v_mfma_f32_16x16x32_bf16 v[86:89], v[166:169], v[192:195], v[86:89]
	v_mfma_f32_16x16x32_bf16 v[62:65], v[158:161], v[200:203], v[62:65]
	v_mfma_f32_16x16x32_bf16 v[54:57], v[166:169], v[200:203], v[54:57]
	v_mfma_f32_16x16x32_bf16 v[30:33], v[158:161], v[208:211], v[30:33]
	v_mfma_f32_16x16x32_bf16 v[26:29], v[166:169], v[208:211], v[26:29]
	v_mfma_f32_16x16x32_bf16 v[14:17], v[158:161], v[218:221], v[14:17]
	v_mfma_f32_16x16x32_bf16 v[10:13], v[166:169], v[218:221], v[10:13]
	s_setprio 0
	s_setprio 1
	v_mfma_f32_16x16x32_bf16 v[74:77], v[172:175], v[188:191], v[74:77]
	v_mfma_f32_16x16x32_bf16 v[66:69], v[180:183], v[188:191], v[66:69]
	v_mfma_f32_16x16x32_bf16 v[42:45], v[172:175], v[196:199], v[42:45]
	v_mfma_f32_16x16x32_bf16 v[34:37], v[180:183], v[196:199], v[34:37]
	v_mfma_f32_16x16x32_bf16 v[22:25], v[172:175], v[204:207], v[22:25]
	v_mfma_f32_16x16x32_bf16 v[18:21], v[180:183], v[204:207], v[18:21]
	v_mfma_f32_16x16x32_bf16 v[6:9], v[172:175], v[214:217], v[6:9]
	v_mfma_f32_16x16x32_bf16 v[2:5], v[180:183], v[214:217], v[2:5]
	v_mfma_f32_16x16x32_bf16 v[74:77], v[176:179], v[192:195], v[74:77]
	v_mfma_f32_16x16x32_bf16 v[66:69], v[184:187], v[192:195], v[66:69]
	v_mfma_f32_16x16x32_bf16 v[42:45], v[176:179], v[200:203], v[42:45]
	v_mfma_f32_16x16x32_bf16 v[34:37], v[184:187], v[200:203], v[34:37]
	v_mfma_f32_16x16x32_bf16 v[22:25], v[176:179], v[208:211], v[22:25]
	v_mfma_f32_16x16x32_bf16 v[18:21], v[184:187], v[208:211], v[18:21]
	v_mfma_f32_16x16x32_bf16 v[6:9], v[176:179], v[218:221], v[6:9]
	v_mfma_f32_16x16x32_bf16 v[2:5], v[184:187], v[218:221], v[2:5]
	s_setprio 0
	s_add_i32 s50, s50, 2
	s_add_u32 s24, s24, 0x100
	s_addc_u32 s25, s25, 0
	s_cmp_gt_u32 s50, 29
	s_barrier
	s_cbranch_scc0 .LBB0_1911
	s_add_u32 s24, s21, 0xffffff00
	s_addc_u32 s25, s45, -1
	s_andn2_b64 vcc, exec, s[2:3]
	s_cbranch_vccnz .LBB0_1902
	v_mov_b32_e32 v2, 0
	s_mov_b32 s4, s14
	s_mov_b32 s6, s16
	s_mov_b64 s[8:9], s[22:23]
	s_mov_b32 s40, s20
	v_mov_b32_e32 v3, v2
	v_mov_b32_e32 v4, v2
	v_mov_b32_e32 v5, v2
	v_mov_b32_e32 v6, v2
	v_mov_b32_e32 v7, v2
	v_mov_b32_e32 v8, v2
	v_mov_b32_e32 v9, v2
	v_mov_b32_e32 v18, v2
	v_mov_b32_e32 v19, v2
	v_mov_b32_e32 v20, v2
	v_mov_b32_e32 v21, v2
	v_mov_b32_e32 v22, v2
	v_mov_b32_e32 v23, v2
	v_mov_b32_e32 v24, v2
	v_mov_b32_e32 v25, v2
	v_mov_b32_e32 v34, v2
	v_mov_b32_e32 v35, v2
	v_mov_b32_e32 v36, v2
	v_mov_b32_e32 v37, v2
	v_mov_b32_e32 v42, v2
	v_mov_b32_e32 v43, v2
	v_mov_b32_e32 v44, v2
	v_mov_b32_e32 v45, v2
	v_mov_b32_e32 v66, v2
	v_mov_b32_e32 v67, v2
	v_mov_b32_e32 v68, v2
	v_mov_b32_e32 v69, v2
	v_mov_b32_e32 v74, v2
	v_mov_b32_e32 v75, v2
	v_mov_b32_e32 v76, v2
	v_mov_b32_e32 v77, v2
	v_mov_b32_e32 v10, v2
	v_mov_b32_e32 v11, v2
	v_mov_b32_e32 v12, v2
	v_mov_b32_e32 v13, v2
	v_mov_b32_e32 v14, v2
	v_mov_b32_e32 v15, v2
	v_mov_b32_e32 v16, v2
	v_mov_b32_e32 v17, v2
	v_mov_b32_e32 v26, v2
	v_mov_b32_e32 v27, v2
	v_mov_b32_e32 v28, v2
	v_mov_b32_e32 v29, v2
	v_mov_b32_e32 v30, v2
	v_mov_b32_e32 v31, v2
	v_mov_b32_e32 v32, v2
	v_mov_b32_e32 v33, v2
	v_mov_b32_e32 v54, v2
	v_mov_b32_e32 v55, v2
	v_mov_b32_e32 v56, v2
	v_mov_b32_e32 v57, v2
	v_mov_b32_e32 v62, v2
	v_mov_b32_e32 v63, v2
	v_mov_b32_e32 v64, v2
	v_mov_b32_e32 v65, v2
	v_mov_b32_e32 v86, v2
	v_mov_b32_e32 v87, v2
	v_mov_b32_e32 v88, v2
	v_mov_b32_e32 v89, v2
	v_mov_b32_e32 v94, v2
	v_mov_b32_e32 v95, v2
	v_mov_b32_e32 v96, v2
	v_mov_b32_e32 v97, v2
	v_mov_b32_e32 v102, v2
	v_mov_b32_e32 v103, v2
	v_mov_b32_e32 v104, v2
	v_mov_b32_e32 v105, v2
	v_mov_b32_e32 v114, v2
	v_mov_b32_e32 v115, v2
	v_mov_b32_e32 v116, v2
	v_mov_b32_e32 v117, v2
	v_mov_b32_e32 v118, v2
	v_mov_b32_e32 v119, v2
	v_mov_b32_e32 v120, v2
	v_mov_b32_e32 v121, v2
	v_mov_b32_e32 v108, v2
	v_mov_b32_e32 v109, v2
	v_mov_b32_e32 v110, v2
	v_mov_b32_e32 v111, v2
	v_mov_b32_e32 v90, v2
	v_mov_b32_e32 v91, v2
	v_mov_b32_e32 v92, v2
	v_mov_b32_e32 v93, v2
	v_mov_b32_e32 v80, v2
	v_mov_b32_e32 v81, v2
	v_mov_b32_e32 v82, v2
	v_mov_b32_e32 v83, v2
	v_mov_b32_e32 v58, v2
	v_mov_b32_e32 v59, v2
	v_mov_b32_e32 v60, v2
	v_mov_b32_e32 v61, v2
	v_mov_b32_e32 v48, v2
	v_mov_b32_e32 v49, v2
	v_mov_b32_e32 v50, v2
	v_mov_b32_e32 v51, v2
	v_mov_b32_e32 v122, v2
	v_mov_b32_e32 v123, v2
	v_mov_b32_e32 v124, v2
	v_mov_b32_e32 v125, v2
	v_mov_b32_e32 v126, v2
	v_mov_b32_e32 v127, v2
	v_mov_b32_e32 v128, v2
	v_mov_b32_e32 v129, v2
	v_mov_b32_e32 v130, v2
	v_mov_b32_e32 v131, v2
	v_mov_b32_e32 v132, v2
	v_mov_b32_e32 v133, v2
	v_mov_b32_e32 v98, v2
	v_mov_b32_e32 v99, v2
	v_mov_b32_e32 v100, v2
	v_mov_b32_e32 v101, v2
	v_mov_b32_e32 v134, v2
	v_mov_b32_e32 v135, v2
	v_mov_b32_e32 v136, v2
	v_mov_b32_e32 v137, v2
	v_mov_b32_e32 v70, v2
	v_mov_b32_e32 v71, v2
	v_mov_b32_e32 v72, v2
	v_mov_b32_e32 v73, v2
	v_mov_b32_e32 v138, v2
	v_mov_b32_e32 v139, v2
	v_mov_b32_e32 v140, v2
	v_mov_b32_e32 v141, v2
	v_mov_b32_e32 v38, v2
	v_mov_b32_e32 v39, v2
	v_mov_b32_e32 v40, v2
	v_mov_b32_e32 v41, v2
	s_mov_b32 s84, s66
	s_andn2_b64 vcc, exec, s[0:1]
	s_cbranch_vccnz .LBB0_1903
